# on top of m,n,k MFMA order: LDS-DMA loads in the 9 K-loops use the SADDR form (SGPR base + 32-bit VGPR offset), removing 16 v_lshl_add_u64 per iteration
# speedup vs baseline: 1.2054x; 1.0083x over previous
.LBB0_1790:
	ds_read_b128 v[146:149], v159
	ds_read_b128 v[150:153], v159 offset:1024
	ds_read_b128 v[164:167], v159 offset:2048
	ds_read_b128 v[168:171], v159 offset:3072
	ds_read_b128 v[172:175], v160
	ds_read_b128 v[176:179], v160 offset:1024
	ds_read_b128 v[186:189], v160 offset:2048
	ds_read_b128 v[190:193], v160 offset:3072
	s_add_u32 s79, s6, 0xfff00080
	s_addc_u32 s80, s7, -1
	s_cmp_eq_u32 s78, 60
	s_cselect_b32 s91, s45, s80
	s_cselect_b32 s90, s74, s79
	s_cselect_b32 s89, s43, s77
	s_cselect_b32 s88, s75, s76
	s_add_i32 m0, s33, 0xc000
	ds_read_b128 v[194:197], v161
	ds_read_b128 v[198:201], v161 offset:1024
	ds_read_b128 v[202:205], v161 offset:2048
	ds_read_b128 v[206:209], v161 offset:3072
	ds_read_b128 v[210:213], v161 offset:4096
	ds_read_b128 v[214:217], v161 offset:5120
	ds_read_b128 v[218:221], v161 offset:6144
	ds_read_b128 v[222:225], v161 offset:7168
	global_load_lds_dwordx4 v138, s[6:7]
	s_add_i32 m0, s33, 0xe000
	s_nop 0
	global_load_lds_dwordx4 v140, s[6:7]
	s_waitcnt vmcnt(8)
	s_waitcnt lgkmcnt(0)
	s_barrier
	s_setprio 1
	s_waitcnt lgkmcnt(0)
	v_mfma_f32_16x16x32_bf16 v[126:129], v[146:149], v[194:197], v[126:129]
	v_mfma_f32_16x16x32_bf16 v[126:129], v[150:153], v[198:201], v[126:129]
	v_mfma_f32_16x16x32_bf16 v[122:125], v[164:167], v[194:197], v[122:125]
	v_mfma_f32_16x16x32_bf16 v[122:125], v[168:171], v[198:201], v[122:125]
	v_mfma_f32_16x16x32_bf16 v[114:117], v[146:149], v[202:205], v[114:117]
	v_mfma_f32_16x16x32_bf16 v[114:117], v[150:153], v[206:209], v[114:117]
	v_mfma_f32_16x16x32_bf16 v[106:109], v[164:167], v[202:205], v[106:109]
	v_mfma_f32_16x16x32_bf16 v[106:109], v[168:171], v[206:209], v[106:109]
	v_mfma_f32_16x16x32_bf16 v[98:101], v[146:149], v[210:213], v[98:101]
	v_mfma_f32_16x16x32_bf16 v[98:101], v[150:153], v[214:217], v[98:101]
	v_mfma_f32_16x16x32_bf16 v[90:93], v[164:167], v[210:213], v[90:93]
	v_mfma_f32_16x16x32_bf16 v[90:93], v[168:171], v[214:217], v[90:93]
	v_mfma_f32_16x16x32_bf16 v[82:85], v[146:149], v[218:221], v[82:85]
	v_mfma_f32_16x16x32_bf16 v[82:85], v[150:153], v[222:225], v[82:85]
	v_mfma_f32_16x16x32_bf16 v[74:77], v[164:167], v[218:221], v[74:77]
	v_mfma_f32_16x16x32_bf16 v[74:77], v[168:171], v[222:225], v[74:77]
	s_setprio 0
	s_setprio 1
	v_mfma_f32_16x16x32_bf16 v[118:121], v[172:175], v[194:197], v[118:121]
	v_mfma_f32_16x16x32_bf16 v[118:121], v[176:179], v[198:201], v[118:121]
	v_mfma_f32_16x16x32_bf16 v[110:113], v[186:189], v[194:197], v[110:113]
	v_mfma_f32_16x16x32_bf16 v[110:113], v[190:193], v[198:201], v[110:113]
	v_mfma_f32_16x16x32_bf16 v[102:105], v[172:175], v[202:205], v[102:105]
	v_mfma_f32_16x16x32_bf16 v[102:105], v[176:179], v[206:209], v[102:105]
	v_mfma_f32_16x16x32_bf16 v[94:97], v[186:189], v[202:205], v[94:97]
	v_mfma_f32_16x16x32_bf16 v[94:97], v[190:193], v[206:209], v[94:97]
	v_mfma_f32_16x16x32_bf16 v[86:89], v[172:175], v[210:213], v[86:89]
	v_mfma_f32_16x16x32_bf16 v[86:89], v[176:179], v[214:217], v[86:89]
	v_mfma_f32_16x16x32_bf16 v[78:81], v[186:189], v[210:213], v[78:81]
	v_mfma_f32_16x16x32_bf16 v[78:81], v[190:193], v[214:217], v[78:81]
	v_mfma_f32_16x16x32_bf16 v[70:73], v[172:175], v[218:221], v[70:73]
	v_mfma_f32_16x16x32_bf16 v[70:73], v[176:179], v[222:225], v[70:73]
	v_mfma_f32_16x16x32_bf16 v[66:69], v[186:189], v[218:221], v[66:69]
	v_mfma_f32_16x16x32_bf16 v[66:69], v[190:193], v[222:225], v[66:69]
	s_setprio 0
	s_barrier
	s_add_i32 s79, s69, s25
	s_add_u32 s98, s88, 0x80
	s_addc_u32 s99, s89, 0
	s_mov_b32 m0, s79
	ds_read_b128 v[194:197], v161 offset:16384
	ds_read_b128 v[198:201], v161 offset:17408
	ds_read_b128 v[202:205], v161 offset:18432
	ds_read_b128 v[206:209], v161 offset:19456
	ds_read_b128 v[210:213], v161 offset:20480
	ds_read_b128 v[214:217], v161 offset:21504
	ds_read_b128 v[218:221], v161 offset:22528
	ds_read_b128 v[222:225], v161 offset:23552
	global_load_lds_dwordx4 v132, s[88:89]
	s_add_i32 m0, s79, 0x2000
	s_add_u32 s80, s88, 0x100000
	s_addc_u32 s81, s89, 0
	s_add_i32 s79, s70, s25
	global_load_lds_dwordx4 v136, s[88:89]
	s_mov_b32 m0, s79
	global_load_lds_dwordx4 v132, s[80:81]
	s_add_i32 m0, s79, 0x2000
	s_nop 0
	global_load_lds_dwordx4 v136, s[80:81]
	s_add_u32 s100, s90, 0x80
	s_addc_u32 s101, s91, 0
	s_mov_b32 m0, s33
	s_nop 0
	global_load_lds_dwordx4 v130, s[90:91]
	s_mov_b32 m0, s35
	s_nop 0
	global_load_lds_dwordx4 v134, s[90:91]
	s_waitcnt vmcnt(8)
	s_waitcnt lgkmcnt(0)
	s_barrier
	s_setprio 1
	s_waitcnt lgkmcnt(0)
	v_mfma_f32_16x16x32_bf16 v[62:65], v[146:149], v[194:197], v[62:65]
	v_mfma_f32_16x16x32_bf16 v[62:65], v[150:153], v[198:201], v[62:65]
	v_mfma_f32_16x16x32_bf16 v[58:61], v[164:167], v[194:197], v[58:61]
	v_mfma_f32_16x16x32_bf16 v[58:61], v[168:171], v[198:201], v[58:61]
	v_mfma_f32_16x16x32_bf16 v[50:53], v[146:149], v[202:205], v[50:53]
	v_mfma_f32_16x16x32_bf16 v[50:53], v[150:153], v[206:209], v[50:53]
	v_mfma_f32_16x16x32_bf16 v[42:45], v[164:167], v[202:205], v[42:45]
	v_mfma_f32_16x16x32_bf16 v[42:45], v[168:171], v[206:209], v[42:45]
	v_mfma_f32_16x16x32_bf16 v[34:37], v[146:149], v[210:213], v[34:37]
	v_mfma_f32_16x16x32_bf16 v[34:37], v[150:153], v[214:217], v[34:37]
	v_mfma_f32_16x16x32_bf16 v[26:29], v[164:167], v[210:213], v[26:29]
	v_mfma_f32_16x16x32_bf16 v[26:29], v[168:171], v[214:217], v[26:29]
	v_mfma_f32_16x16x32_bf16 v[18:21], v[146:149], v[218:221], v[18:21]
	v_mfma_f32_16x16x32_bf16 v[18:21], v[150:153], v[222:225], v[18:21]
	v_mfma_f32_16x16x32_bf16 v[10:13], v[164:167], v[218:221], v[10:13]
	v_mfma_f32_16x16x32_bf16 v[10:13], v[168:171], v[222:225], v[10:13]
	s_setprio 0
	s_setprio 1
	v_mfma_f32_16x16x32_bf16 v[54:57], v[172:175], v[194:197], v[54:57]
	v_mfma_f32_16x16x32_bf16 v[54:57], v[176:179], v[198:201], v[54:57]
	v_mfma_f32_16x16x32_bf16 v[46:49], v[186:189], v[194:197], v[46:49]
	v_mfma_f32_16x16x32_bf16 v[46:49], v[190:193], v[198:201], v[46:49]
	v_mfma_f32_16x16x32_bf16 v[38:41], v[172:175], v[202:205], v[38:41]
	v_mfma_f32_16x16x32_bf16 v[38:41], v[176:179], v[206:209], v[38:41]
	v_mfma_f32_16x16x32_bf16 v[30:33], v[186:189], v[202:205], v[30:33]
	v_mfma_f32_16x16x32_bf16 v[30:33], v[190:193], v[206:209], v[30:33]
	v_mfma_f32_16x16x32_bf16 v[22:25], v[172:175], v[210:213], v[22:25]
	v_mfma_f32_16x16x32_bf16 v[22:25], v[176:179], v[214:217], v[22:25]
	v_mfma_f32_16x16x32_bf16 v[14:17], v[186:189], v[210:213], v[14:17]
	v_mfma_f32_16x16x32_bf16 v[14:17], v[190:193], v[214:217], v[14:17]
	v_mfma_f32_16x16x32_bf16 v[6:9], v[172:175], v[218:221], v[6:9]
	v_mfma_f32_16x16x32_bf16 v[6:9], v[176:179], v[222:225], v[6:9]
	v_mfma_f32_16x16x32_bf16 v[2:5], v[186:189], v[218:221], v[2:5]
	v_mfma_f32_16x16x32_bf16 v[2:5], v[190:193], v[222:225], v[2:5]
	s_setprio 0
	s_barrier
	s_add_i32 s79, 0, 0x18000
	s_add_i32 s82, 0, 0x1c000
	v_add_u32_e32 v168, s79, v155
	v_add_u32_e32 v183, s82, v155
	ds_read_b128 v[146:149], v168
	ds_read_b128 v[150:153], v168 offset:1024
	ds_read_b128 v[164:167], v168 offset:2048
	ds_read_b128 v[168:171], v168 offset:3072
	ds_read_b128 v[172:175], v183
	ds_read_b128 v[176:179], v183 offset:1024
	ds_read_b128 v[186:189], v183 offset:2048
	ds_read_b128 v[190:193], v183 offset:3072
	s_add_u32 s80, s90, 0x100000
	s_addc_u32 s81, s91, 0
	s_mov_b32 m0, s59
	ds_read_b128 v[194:197], v161 offset:32768
	ds_read_b128 v[198:201], v161 offset:33792
	ds_read_b128 v[202:205], v161 offset:34816
	ds_read_b128 v[206:209], v161 offset:35840
	ds_read_b128 v[210:213], v161 offset:36864
	ds_read_b128 v[214:217], v161 offset:37888
	ds_read_b128 v[218:221], v161 offset:38912
	ds_read_b128 v[222:225], v161 offset:39936
	global_load_lds_dwordx4 v130, s[80:81]
	s_mov_b32 m0, s62
	s_nop 0
	global_load_lds_dwordx4 v134, s[80:81]
	s_waitcnt vmcnt(8)
	s_waitcnt lgkmcnt(0)
	s_barrier
	s_setprio 1
	s_waitcnt lgkmcnt(0)
	v_mfma_f32_16x16x32_bf16 v[126:129], v[146:149], v[194:197], v[126:129]
	v_mfma_f32_16x16x32_bf16 v[126:129], v[150:153], v[198:201], v[126:129]
	v_mfma_f32_16x16x32_bf16 v[122:125], v[164:167], v[194:197], v[122:125]
	v_mfma_f32_16x16x32_bf16 v[122:125], v[168:171], v[198:201], v[122:125]
	v_mfma_f32_16x16x32_bf16 v[114:117], v[146:149], v[202:205], v[114:117]
	v_mfma_f32_16x16x32_bf16 v[114:117], v[150:153], v[206:209], v[114:117]
	v_mfma_f32_16x16x32_bf16 v[106:109], v[164:167], v[202:205], v[106:109]
	v_mfma_f32_16x16x32_bf16 v[106:109], v[168:171], v[206:209], v[106:109]
	v_mfma_f32_16x16x32_bf16 v[98:101], v[146:149], v[210:213], v[98:101]
	v_mfma_f32_16x16x32_bf16 v[98:101], v[150:153], v[214:217], v[98:101]
	v_mfma_f32_16x16x32_bf16 v[90:93], v[164:167], v[210:213], v[90:93]
	v_mfma_f32_16x16x32_bf16 v[90:93], v[168:171], v[214:217], v[90:93]
	v_mfma_f32_16x16x32_bf16 v[82:85], v[146:149], v[218:221], v[82:85]
	v_mfma_f32_16x16x32_bf16 v[82:85], v[150:153], v[222:225], v[82:85]
	v_mfma_f32_16x16x32_bf16 v[74:77], v[164:167], v[218:221], v[74:77]
	v_mfma_f32_16x16x32_bf16 v[74:77], v[168:171], v[222:225], v[74:77]
	s_setprio 0
	s_setprio 1
	v_mfma_f32_16x16x32_bf16 v[118:121], v[172:175], v[194:197], v[118:121]
	v_mfma_f32_16x16x32_bf16 v[118:121], v[176:179], v[198:201], v[118:121]
	v_mfma_f32_16x16x32_bf16 v[110:113], v[186:189], v[194:197], v[110:113]
	v_mfma_f32_16x16x32_bf16 v[110:113], v[190:193], v[198:201], v[110:113]
	v_mfma_f32_16x16x32_bf16 v[102:105], v[172:175], v[202:205], v[102:105]
	v_mfma_f32_16x16x32_bf16 v[102:105], v[176:179], v[206:209], v[102:105]
	v_mfma_f32_16x16x32_bf16 v[94:97], v[186:189], v[202:205], v[94:97]
	v_mfma_f32_16x16x32_bf16 v[94:97], v[190:193], v[206:209], v[94:97]
	v_mfma_f32_16x16x32_bf16 v[86:89], v[172:175], v[210:213], v[86:89]
	v_mfma_f32_16x16x32_bf16 v[86:89], v[176:179], v[214:217], v[86:89]
	v_mfma_f32_16x16x32_bf16 v[78:81], v[186:189], v[210:213], v[78:81]
	v_mfma_f32_16x16x32_bf16 v[78:81], v[190:193], v[214:217], v[78:81]
	v_mfma_f32_16x16x32_bf16 v[70:73], v[172:175], v[218:221], v[70:73]
	v_mfma_f32_16x16x32_bf16 v[70:73], v[176:179], v[222:225], v[70:73]
	v_mfma_f32_16x16x32_bf16 v[66:69], v[186:189], v[218:221], v[66:69]
	v_mfma_f32_16x16x32_bf16 v[66:69], v[190:193], v[222:225], v[66:69]
	s_setprio 0
	s_barrier
	s_add_i32 s79, s79, s25
	s_mov_b32 m0, s79
	ds_read_b128 v[194:197], v161 offset:49152
	ds_read_b128 v[198:201], v161 offset:50176
	ds_read_b128 v[202:205], v161 offset:51200
	ds_read_b128 v[206:209], v161 offset:52224
	ds_read_b128 v[210:213], v161 offset:53248
	ds_read_b128 v[214:217], v161 offset:54272
	ds_read_b128 v[218:221], v161 offset:55296
	ds_read_b128 v[222:225], v161 offset:56320
	global_load_lds_dwordx4 v132, s[98:99]
	s_add_i32 m0, s79, 0x2000
	s_add_u32 s80, s88, 0x100080
	s_addc_u32 s81, s89, 0
	s_add_i32 s79, s82, s25
	global_load_lds_dwordx4 v136, s[98:99]
	s_mov_b32 m0, s79
	s_nop 0
	global_load_lds_dwordx4 v132, s[80:81]
	s_add_i32 m0, s79, 0x2000
	s_nop 0
	global_load_lds_dwordx4 v136, s[80:81]
	s_mov_b32 m0, s66
	s_nop 0
	global_load_lds_dwordx4 v130, s[100:101]
	s_mov_b32 m0, s67
	s_nop 0
	global_load_lds_dwordx4 v134, s[100:101]
	s_waitcnt vmcnt(8)
	s_waitcnt lgkmcnt(0)
	s_barrier
	s_setprio 1
	s_waitcnt lgkmcnt(0)
	v_mfma_f32_16x16x32_bf16 v[62:65], v[146:149], v[194:197], v[62:65]
	v_mfma_f32_16x16x32_bf16 v[62:65], v[150:153], v[198:201], v[62:65]
	v_mfma_f32_16x16x32_bf16 v[58:61], v[164:167], v[194:197], v[58:61]
	v_mfma_f32_16x16x32_bf16 v[58:61], v[168:171], v[198:201], v[58:61]
	v_mfma_f32_16x16x32_bf16 v[50:53], v[146:149], v[202:205], v[50:53]
	v_mfma_f32_16x16x32_bf16 v[50:53], v[150:153], v[206:209], v[50:53]
	v_mfma_f32_16x16x32_bf16 v[42:45], v[164:167], v[202:205], v[42:45]
	v_mfma_f32_16x16x32_bf16 v[42:45], v[168:171], v[206:209], v[42:45]
	v_mfma_f32_16x16x32_bf16 v[34:37], v[146:149], v[210:213], v[34:37]
	v_mfma_f32_16x16x32_bf16 v[34:37], v[150:153], v[214:217], v[34:37]
	v_mfma_f32_16x16x32_bf16 v[26:29], v[164:167], v[210:213], v[26:29]
	v_mfma_f32_16x16x32_bf16 v[26:29], v[168:171], v[214:217], v[26:29]
	v_mfma_f32_16x16x32_bf16 v[18:21], v[146:149], v[218:221], v[18:21]
	v_mfma_f32_16x16x32_bf16 v[18:21], v[150:153], v[222:225], v[18:21]
	v_mfma_f32_16x16x32_bf16 v[10:13], v[164:167], v[218:221], v[10:13]
	v_mfma_f32_16x16x32_bf16 v[10:13], v[168:171], v[222:225], v[10:13]
	s_setprio 0
	s_setprio 1
	v_mfma_f32_16x16x32_bf16 v[54:57], v[172:175], v[194:197], v[54:57]
	v_mfma_f32_16x16x32_bf16 v[54:57], v[176:179], v[198:201], v[54:57]
	v_mfma_f32_16x16x32_bf16 v[46:49], v[186:189], v[194:197], v[46:49]
	v_mfma_f32_16x16x32_bf16 v[46:49], v[190:193], v[198:201], v[46:49]
	v_mfma_f32_16x16x32_bf16 v[38:41], v[172:175], v[202:205], v[38:41]
	v_mfma_f32_16x16x32_bf16 v[38:41], v[176:179], v[206:209], v[38:41]
	v_mfma_f32_16x16x32_bf16 v[30:33], v[186:189], v[202:205], v[30:33]
	v_mfma_f32_16x16x32_bf16 v[30:33], v[190:193], v[206:209], v[30:33]
	v_mfma_f32_16x16x32_bf16 v[22:25], v[172:175], v[210:213], v[22:25]
	v_mfma_f32_16x16x32_bf16 v[22:25], v[176:179], v[214:217], v[22:25]
	v_mfma_f32_16x16x32_bf16 v[14:17], v[186:189], v[210:213], v[14:17]
	v_mfma_f32_16x16x32_bf16 v[14:17], v[190:193], v[214:217], v[14:17]
	v_mfma_f32_16x16x32_bf16 v[6:9], v[172:175], v[218:221], v[6:9]
	v_mfma_f32_16x16x32_bf16 v[6:9], v[176:179], v[222:225], v[6:9]
	v_mfma_f32_16x16x32_bf16 v[2:5], v[186:189], v[218:221], v[2:5]
	v_mfma_f32_16x16x32_bf16 v[2:5], v[190:193], v[222:225], v[2:5]
	s_setprio 0
	s_barrier
	s_add_i32 s78, s78, 2
	s_add_u32 s6, s6, 0x100
	s_addc_u32 s7, s7, 0
	s_add_u32 s76, s76, 0x100
	s_addc_u32 s77, s77, 0
	s_cmp_gt_u32 s78, 61
	s_cbranch_scc0 .LBB0_1790
	s_and_b64 vcc, exec, s[40:41]
	s_cbranch_vccz .LBB0_1793
	s_barrier

.LBB0_2109:
	ds_read_b128 v[130:133], v155
	ds_read_b128 v[134:137], v155 offset:1024
	ds_read_b128 v[138:141], v155 offset:2048
	ds_read_b128 v[142:145], v155 offset:3072
	ds_read_b128 v[166:169], v176
	ds_read_b128 v[170:173], v176 offset:1024
	ds_read_b128 v[186:189], v176 offset:2048
	ds_read_b128 v[190:193], v176 offset:3072
	s_add_u32 s74, s50, 0xfff00080
	s_addc_u32 s75, s51, -1
	s_cmp_eq_u32 s73, 60
	s_cselect_b32 s85, s26, s75
	s_cselect_b32 s84, s45, s74
	s_cselect_b32 s83, s43, s72
	s_cselect_b32 s82, s70, s71
	s_add_i32 m0, s23, 0xc000
	ds_read_b128 v[194:197], v177
	ds_read_b128 v[198:201], v177 offset:1024
	ds_read_b128 v[202:205], v177 offset:2048
	ds_read_b128 v[206:209], v177 offset:3072
	ds_read_b128 v[210:213], v177 offset:4096
	ds_read_b128 v[214:217], v177 offset:5120
	ds_read_b128 v[218:221], v177 offset:6144
	ds_read_b128 v[222:225], v177 offset:7168
	global_load_lds_dwordx4 v158, s[50:51]
	s_add_i32 m0, s23, 0xe000
	s_nop 0
	global_load_lds_dwordx4 v160, s[50:51]
	s_waitcnt vmcnt(8)
	s_waitcnt lgkmcnt(0)
	s_barrier
	s_setprio 1
	s_waitcnt lgkmcnt(0)
	v_mfma_f32_16x16x32_bf16 v[126:129], v[130:133], v[194:197], v[126:129]
	v_mfma_f32_16x16x32_bf16 v[126:129], v[134:137], v[198:201], v[126:129]
	v_mfma_f32_16x16x32_bf16 v[122:125], v[138:141], v[194:197], v[122:125]
	v_mfma_f32_16x16x32_bf16 v[122:125], v[142:145], v[198:201], v[122:125]
	v_mfma_f32_16x16x32_bf16 v[110:113], v[130:133], v[202:205], v[110:113]
	v_mfma_f32_16x16x32_bf16 v[110:113], v[134:137], v[206:209], v[110:113]
	v_mfma_f32_16x16x32_bf16 v[106:109], v[138:141], v[202:205], v[106:109]
	v_mfma_f32_16x16x32_bf16 v[106:109], v[142:145], v[206:209], v[106:109]
	v_mfma_f32_16x16x32_bf16 v[94:97], v[130:133], v[210:213], v[94:97]
	v_mfma_f32_16x16x32_bf16 v[94:97], v[134:137], v[214:217], v[94:97]
	v_mfma_f32_16x16x32_bf16 v[90:93], v[138:141], v[210:213], v[90:93]
	v_mfma_f32_16x16x32_bf16 v[90:93], v[142:145], v[214:217], v[90:93]
	v_mfma_f32_16x16x32_bf16 v[78:81], v[130:133], v[218:221], v[78:81]
	v_mfma_f32_16x16x32_bf16 v[78:81], v[134:137], v[222:225], v[78:81]
	v_mfma_f32_16x16x32_bf16 v[74:77], v[138:141], v[218:221], v[74:77]
	v_mfma_f32_16x16x32_bf16 v[74:77], v[142:145], v[222:225], v[74:77]
	s_setprio 0
	s_setprio 1
	v_mfma_f32_16x16x32_bf16 v[118:121], v[166:169], v[194:197], v[118:121]
	v_mfma_f32_16x16x32_bf16 v[118:121], v[170:173], v[198:201], v[118:121]
	v_mfma_f32_16x16x32_bf16 v[114:117], v[186:189], v[194:197], v[114:117]
	v_mfma_f32_16x16x32_bf16 v[114:117], v[190:193], v[198:201], v[114:117]
	v_mfma_f32_16x16x32_bf16 v[102:105], v[166:169], v[202:205], v[102:105]
	v_mfma_f32_16x16x32_bf16 v[102:105], v[170:173], v[206:209], v[102:105]
	v_mfma_f32_16x16x32_bf16 v[98:101], v[186:189], v[202:205], v[98:101]
	v_mfma_f32_16x16x32_bf16 v[98:101], v[190:193], v[206:209], v[98:101]
	v_mfma_f32_16x16x32_bf16 v[86:89], v[166:169], v[210:213], v[86:89]
	v_mfma_f32_16x16x32_bf16 v[86:89], v[170:173], v[214:217], v[86:89]
	v_mfma_f32_16x16x32_bf16 v[82:85], v[186:189], v[210:213], v[82:85]
	v_mfma_f32_16x16x32_bf16 v[82:85], v[190:193], v[214:217], v[82:85]
	v_mfma_f32_16x16x32_bf16 v[70:73], v[166:169], v[218:221], v[70:73]
	v_mfma_f32_16x16x32_bf16 v[70:73], v[170:173], v[222:225], v[70:73]
	v_mfma_f32_16x16x32_bf16 v[66:69], v[186:189], v[218:221], v[66:69]
	v_mfma_f32_16x16x32_bf16 v[66:69], v[190:193], v[222:225], v[66:69]
	s_setprio 0
	s_barrier
	s_add_i32 s74, s67, s3
	s_add_u32 s98, s82, 0x80
	s_addc_u32 s99, s83, 0
	s_mov_b32 m0, s74
	ds_read_b128 v[194:197], v177 offset:16384
	ds_read_b128 v[198:201], v177 offset:17408
	ds_read_b128 v[202:205], v177 offset:18432
	ds_read_b128 v[206:209], v177 offset:19456
	ds_read_b128 v[210:213], v177 offset:20480
	ds_read_b128 v[214:217], v177 offset:21504
	ds_read_b128 v[218:221], v177 offset:22528
	ds_read_b128 v[222:225], v177 offset:23552
	global_load_lds_dwordx4 v148, s[82:83]
	s_add_i32 m0, s74, 0x2000
	s_add_u32 s74, s82, 0x100000
	s_addc_u32 s75, s83, 0
	s_add_i32 s76, s68, s3
	global_load_lds_dwordx4 v152, s[82:83]
	s_mov_b32 m0, s76
	global_load_lds_dwordx4 v148, s[74:75]
	s_add_i32 m0, s76, 0x2000
	s_nop 0
	global_load_lds_dwordx4 v152, s[74:75]
	s_add_u32 s100, s84, 0x80
	s_addc_u32 s101, s85, 0
	s_mov_b32 m0, s23
	s_nop 0
	global_load_lds_dwordx4 v146, s[84:85]
	s_mov_b32 m0, s25
	s_nop 0
	global_load_lds_dwordx4 v150, s[84:85]
	s_waitcnt vmcnt(8)
	s_waitcnt lgkmcnt(0)
	s_barrier
	s_setprio 1
	s_waitcnt lgkmcnt(0)
	v_mfma_f32_16x16x32_bf16 v[62:65], v[130:133], v[194:197], v[62:65]
	v_mfma_f32_16x16x32_bf16 v[62:65], v[134:137], v[198:201], v[62:65]
	v_mfma_f32_16x16x32_bf16 v[58:61], v[138:141], v[194:197], v[58:61]
	v_mfma_f32_16x16x32_bf16 v[58:61], v[142:145], v[198:201], v[58:61]
	v_mfma_f32_16x16x32_bf16 v[46:49], v[130:133], v[202:205], v[46:49]
	v_mfma_f32_16x16x32_bf16 v[46:49], v[134:137], v[206:209], v[46:49]
	v_mfma_f32_16x16x32_bf16 v[42:45], v[138:141], v[202:205], v[42:45]
	v_mfma_f32_16x16x32_bf16 v[42:45], v[142:145], v[206:209], v[42:45]
	v_mfma_f32_16x16x32_bf16 v[30:33], v[130:133], v[210:213], v[30:33]
	v_mfma_f32_16x16x32_bf16 v[30:33], v[134:137], v[214:217], v[30:33]
	v_mfma_f32_16x16x32_bf16 v[26:29], v[138:141], v[210:213], v[26:29]
	v_mfma_f32_16x16x32_bf16 v[26:29], v[142:145], v[214:217], v[26:29]
	v_mfma_f32_16x16x32_bf16 v[14:17], v[130:133], v[218:221], v[14:17]
	v_mfma_f32_16x16x32_bf16 v[14:17], v[134:137], v[222:225], v[14:17]
	v_mfma_f32_16x16x32_bf16 v[10:13], v[138:141], v[218:221], v[10:13]
	v_mfma_f32_16x16x32_bf16 v[10:13], v[142:145], v[222:225], v[10:13]
	s_setprio 0
	s_setprio 1
	v_mfma_f32_16x16x32_bf16 v[54:57], v[166:169], v[194:197], v[54:57]
	v_mfma_f32_16x16x32_bf16 v[54:57], v[170:173], v[198:201], v[54:57]
	v_mfma_f32_16x16x32_bf16 v[50:53], v[186:189], v[194:197], v[50:53]
	v_mfma_f32_16x16x32_bf16 v[50:53], v[190:193], v[198:201], v[50:53]
	v_mfma_f32_16x16x32_bf16 v[38:41], v[166:169], v[202:205], v[38:41]
	v_mfma_f32_16x16x32_bf16 v[38:41], v[170:173], v[206:209], v[38:41]
	v_mfma_f32_16x16x32_bf16 v[34:37], v[186:189], v[202:205], v[34:37]
	v_mfma_f32_16x16x32_bf16 v[34:37], v[190:193], v[206:209], v[34:37]
	v_mfma_f32_16x16x32_bf16 v[22:25], v[166:169], v[210:213], v[22:25]
	v_mfma_f32_16x16x32_bf16 v[22:25], v[170:173], v[214:217], v[22:25]
	v_mfma_f32_16x16x32_bf16 v[18:21], v[186:189], v[210:213], v[18:21]
	v_mfma_f32_16x16x32_bf16 v[18:21], v[190:193], v[214:217], v[18:21]
	v_mfma_f32_16x16x32_bf16 v[6:9], v[166:169], v[218:221], v[6:9]
	v_mfma_f32_16x16x32_bf16 v[6:9], v[170:173], v[222:225], v[6:9]
	v_mfma_f32_16x16x32_bf16 v[2:5], v[186:189], v[218:221], v[2:5]
	v_mfma_f32_16x16x32_bf16 v[2:5], v[190:193], v[222:225], v[2:5]
	s_setprio 0
	s_barrier
	s_add_i32 s76, 0, 0x18000
	s_add_i32 s77, 0, 0x1c000
	v_add_u32_e32 v142, s76, v174
	v_add_u32_e32 v179, s77, v174
	ds_read_b128 v[130:133], v142
	ds_read_b128 v[134:137], v142 offset:1024
	ds_read_b128 v[138:141], v142 offset:2048
	ds_read_b128 v[142:145], v142 offset:3072
	ds_read_b128 v[166:169], v179
	ds_read_b128 v[170:173], v179 offset:1024
	ds_read_b128 v[186:189], v179 offset:2048
	ds_read_b128 v[190:193], v179 offset:3072
	s_add_u32 s74, s84, 0x100000
	s_addc_u32 s75, s85, 0
	s_mov_b32 m0, s33
	ds_read_b128 v[194:197], v177 offset:32768
	ds_read_b128 v[198:201], v177 offset:33792
	ds_read_b128 v[202:205], v177 offset:34816
	ds_read_b128 v[206:209], v177 offset:35840
	ds_read_b128 v[210:213], v177 offset:36864
	ds_read_b128 v[214:217], v177 offset:37888
	ds_read_b128 v[218:221], v177 offset:38912
	ds_read_b128 v[222:225], v177 offset:39936
	global_load_lds_dwordx4 v146, s[74:75]
	s_mov_b32 m0, s35
	s_nop 0
	global_load_lds_dwordx4 v150, s[74:75]
	s_waitcnt vmcnt(8)
	s_waitcnt lgkmcnt(0)
	s_barrier
	s_setprio 1
	s_waitcnt lgkmcnt(0)
	v_mfma_f32_16x16x32_bf16 v[126:129], v[130:133], v[194:197], v[126:129]
	v_mfma_f32_16x16x32_bf16 v[126:129], v[134:137], v[198:201], v[126:129]
	v_mfma_f32_16x16x32_bf16 v[122:125], v[138:141], v[194:197], v[122:125]
	v_mfma_f32_16x16x32_bf16 v[122:125], v[142:145], v[198:201], v[122:125]
	v_mfma_f32_16x16x32_bf16 v[110:113], v[130:133], v[202:205], v[110:113]
	v_mfma_f32_16x16x32_bf16 v[110:113], v[134:137], v[206:209], v[110:113]
	v_mfma_f32_16x16x32_bf16 v[106:109], v[138:141], v[202:205], v[106:109]
	v_mfma_f32_16x16x32_bf16 v[106:109], v[142:145], v[206:209], v[106:109]
	v_mfma_f32_16x16x32_bf16 v[94:97], v[130:133], v[210:213], v[94:97]
	v_mfma_f32_16x16x32_bf16 v[94:97], v[134:137], v[214:217], v[94:97]
	v_mfma_f32_16x16x32_bf16 v[90:93], v[138:141], v[210:213], v[90:93]
	v_mfma_f32_16x16x32_bf16 v[90:93], v[142:145], v[214:217], v[90:93]
	v_mfma_f32_16x16x32_bf16 v[78:81], v[130:133], v[218:221], v[78:81]
	v_mfma_f32_16x16x32_bf16 v[78:81], v[134:137], v[222:225], v[78:81]
	v_mfma_f32_16x16x32_bf16 v[74:77], v[138:141], v[218:221], v[74:77]
	v_mfma_f32_16x16x32_bf16 v[74:77], v[142:145], v[222:225], v[74:77]
	s_setprio 0
	s_setprio 1
	v_mfma_f32_16x16x32_bf16 v[118:121], v[166:169], v[194:197], v[118:121]
	v_mfma_f32_16x16x32_bf16 v[118:121], v[170:173], v[198:201], v[118:121]
	v_mfma_f32_16x16x32_bf16 v[114:117], v[186:189], v[194:197], v[114:117]
	v_mfma_f32_16x16x32_bf16 v[114:117], v[190:193], v[198:201], v[114:117]
	v_mfma_f32_16x16x32_bf16 v[102:105], v[166:169], v[202:205], v[102:105]
	v_mfma_f32_16x16x32_bf16 v[102:105], v[170:173], v[206:209], v[102:105]
	v_mfma_f32_16x16x32_bf16 v[98:101], v[186:189], v[202:205], v[98:101]
	v_mfma_f32_16x16x32_bf16 v[98:101], v[190:193], v[206:209], v[98:101]
	v_mfma_f32_16x16x32_bf16 v[86:89], v[166:169], v[210:213], v[86:89]
	v_mfma_f32_16x16x32_bf16 v[86:89], v[170:173], v[214:217], v[86:89]
	v_mfma_f32_16x16x32_bf16 v[82:85], v[186:189], v[210:213], v[82:85]
	v_mfma_f32_16x16x32_bf16 v[82:85], v[190:193], v[214:217], v[82:85]
	v_mfma_f32_16x16x32_bf16 v[70:73], v[166:169], v[218:221], v[70:73]
	v_mfma_f32_16x16x32_bf16 v[70:73], v[170:173], v[222:225], v[70:73]
	v_mfma_f32_16x16x32_bf16 v[66:69], v[186:189], v[218:221], v[66:69]
	v_mfma_f32_16x16x32_bf16 v[66:69], v[190:193], v[222:225], v[66:69]
	s_setprio 0
	s_barrier
	s_add_i32 s74, s76, s3
	s_mov_b32 m0, s74
	ds_read_b128 v[194:197], v177 offset:49152
	ds_read_b128 v[198:201], v177 offset:50176
	ds_read_b128 v[202:205], v177 offset:51200
	ds_read_b128 v[206:209], v177 offset:52224
	ds_read_b128 v[210:213], v177 offset:53248
	ds_read_b128 v[214:217], v177 offset:54272
	ds_read_b128 v[218:221], v177 offset:55296
	ds_read_b128 v[222:225], v177 offset:56320
	global_load_lds_dwordx4 v148, s[98:99]
	s_add_i32 m0, s74, 0x2000
	s_add_u32 s74, s82, 0x100080
	s_addc_u32 s75, s83, 0
	s_add_i32 s76, s77, s3
	global_load_lds_dwordx4 v152, s[98:99]
	s_mov_b32 m0, s76
	s_nop 0
	global_load_lds_dwordx4 v148, s[74:75]
	s_add_i32 m0, s76, 0x2000
	s_nop 0
	global_load_lds_dwordx4 v152, s[74:75]
	s_mov_b32 m0, s62
	s_nop 0
	global_load_lds_dwordx4 v146, s[100:101]
	s_mov_b32 m0, s63
	s_nop 0
	global_load_lds_dwordx4 v150, s[100:101]
	s_waitcnt vmcnt(8)
	s_waitcnt lgkmcnt(0)
	s_barrier
	s_setprio 1
	s_waitcnt lgkmcnt(0)
	v_mfma_f32_16x16x32_bf16 v[62:65], v[130:133], v[194:197], v[62:65]
	v_mfma_f32_16x16x32_bf16 v[62:65], v[134:137], v[198:201], v[62:65]
	v_mfma_f32_16x16x32_bf16 v[58:61], v[138:141], v[194:197], v[58:61]
	v_mfma_f32_16x16x32_bf16 v[58:61], v[142:145], v[198:201], v[58:61]
	v_mfma_f32_16x16x32_bf16 v[46:49], v[130:133], v[202:205], v[46:49]
	v_mfma_f32_16x16x32_bf16 v[46:49], v[134:137], v[206:209], v[46:49]
	v_mfma_f32_16x16x32_bf16 v[42:45], v[138:141], v[202:205], v[42:45]
	v_mfma_f32_16x16x32_bf16 v[42:45], v[142:145], v[206:209], v[42:45]
	v_mfma_f32_16x16x32_bf16 v[30:33], v[130:133], v[210:213], v[30:33]
	v_mfma_f32_16x16x32_bf16 v[30:33], v[134:137], v[214:217], v[30:33]
	v_mfma_f32_16x16x32_bf16 v[26:29], v[138:141], v[210:213], v[26:29]
	v_mfma_f32_16x16x32_bf16 v[26:29], v[142:145], v[214:217], v[26:29]
	v_mfma_f32_16x16x32_bf16 v[14:17], v[130:133], v[218:221], v[14:17]
	v_mfma_f32_16x16x32_bf16 v[14:17], v[134:137], v[222:225], v[14:17]
	v_mfma_f32_16x16x32_bf16 v[10:13], v[138:141], v[218:221], v[10:13]
	v_mfma_f32_16x16x32_bf16 v[10:13], v[142:145], v[222:225], v[10:13]
	s_setprio 0
	s_setprio 1
	v_mfma_f32_16x16x32_bf16 v[54:57], v[166:169], v[194:197], v[54:57]
	v_mfma_f32_16x16x32_bf16 v[54:57], v[170:173], v[198:201], v[54:57]
	v_mfma_f32_16x16x32_bf16 v[50:53], v[186:189], v[194:197], v[50:53]
	v_mfma_f32_16x16x32_bf16 v[50:53], v[190:193], v[198:201], v[50:53]
	v_mfma_f32_16x16x32_bf16 v[38:41], v[166:169], v[202:205], v[38:41]
	v_mfma_f32_16x16x32_bf16 v[38:41], v[170:173], v[206:209], v[38:41]
	v_mfma_f32_16x16x32_bf16 v[34:37], v[186:189], v[202:205], v[34:37]
	v_mfma_f32_16x16x32_bf16 v[34:37], v[190:193], v[206:209], v[34:37]
	v_mfma_f32_16x16x32_bf16 v[22:25], v[166:169], v[210:213], v[22:25]
	v_mfma_f32_16x16x32_bf16 v[22:25], v[170:173], v[214:217], v[22:25]
	v_mfma_f32_16x16x32_bf16 v[18:21], v[186:189], v[210:213], v[18:21]
	v_mfma_f32_16x16x32_bf16 v[18:21], v[190:193], v[214:217], v[18:21]
	v_mfma_f32_16x16x32_bf16 v[6:9], v[166:169], v[218:221], v[6:9]
	v_mfma_f32_16x16x32_bf16 v[6:9], v[170:173], v[222:225], v[6:9]
	v_mfma_f32_16x16x32_bf16 v[2:5], v[186:189], v[218:221], v[2:5]
	v_mfma_f32_16x16x32_bf16 v[2:5], v[190:193], v[222:225], v[2:5]
	s_setprio 0
	s_barrier
	s_add_i32 s73, s73, 2
	s_add_u32 s50, s50, 0x100
	s_addc_u32 s51, s51, 0
	s_add_u32 s71, s71, 0x100
	s_addc_u32 s72, s72, 0
	s_cmp_gt_u32 s73, 61
	s_cbranch_scc0 .LBB0_2109
	s_and_b64 vcc, exec, s[40:41]
	s_cbranch_vccz .LBB0_2112
	s_barrier

.LBB0_2212:
	ds_read_b128 v[150:153], v162
	ds_read_b128 v[168:171], v162 offset:1024
	ds_read_b128 v[172:175], v162 offset:2048
	ds_read_b128 v[176:179], v162 offset:3072
	ds_read_b128 v[186:189], v163
	ds_read_b128 v[190:193], v163 offset:1024
	ds_read_b128 v[194:197], v163 offset:2048
	ds_read_b128 v[198:201], v163 offset:3072
	s_add_u32 s50, s6, 0xfff00080
	s_addc_u32 s51, s7, -1
	s_cmp_eq_u32 s79, 60
	s_cselect_b32 s81, s45, s51
	s_cselect_b32 s80, s75, s50
	s_cselect_b32 s51, s43, s78
	s_cselect_b32 s50, s76, s77
	s_add_i32 m0, s33, 0xc000
	ds_read_b128 v[202:205], v164
	ds_read_b128 v[206:209], v164 offset:1024
	ds_read_b128 v[210:213], v164 offset:2048
	ds_read_b128 v[214:217], v164 offset:3072
	ds_read_b128 v[218:221], v164 offset:4096
	ds_read_b128 v[222:225], v164 offset:5120
	ds_read_b128 v[226:229], v164 offset:6144
	ds_read_b128 v[230:233], v164 offset:7168
	global_load_lds_dwordx4 v142, s[6:7]
	s_add_i32 m0, s33, 0xe000
	s_nop 0
	global_load_lds_dwordx4 v144, s[6:7]
	s_waitcnt vmcnt(8)
	s_waitcnt lgkmcnt(0)
	s_barrier
	s_setprio 1
	s_waitcnt lgkmcnt(0)
	v_mfma_f32_16x16x32_bf16 v[126:129], v[150:153], v[202:205], v[126:129]
	v_mfma_f32_16x16x32_bf16 v[126:129], v[168:171], v[206:209], v[126:129]
	v_mfma_f32_16x16x32_bf16 v[118:121], v[172:175], v[202:205], v[118:121]
	v_mfma_f32_16x16x32_bf16 v[118:121], v[176:179], v[206:209], v[118:121]
	v_mfma_f32_16x16x32_bf16 v[110:113], v[150:153], v[210:213], v[110:113]
	v_mfma_f32_16x16x32_bf16 v[110:113], v[168:171], v[214:217], v[110:113]
	v_mfma_f32_16x16x32_bf16 v[102:105], v[172:175], v[210:213], v[102:105]
	v_mfma_f32_16x16x32_bf16 v[102:105], v[176:179], v[214:217], v[102:105]
	v_mfma_f32_16x16x32_bf16 v[94:97], v[150:153], v[218:221], v[94:97]
	v_mfma_f32_16x16x32_bf16 v[94:97], v[168:171], v[222:225], v[94:97]
	v_mfma_f32_16x16x32_bf16 v[86:89], v[172:175], v[218:221], v[86:89]
	v_mfma_f32_16x16x32_bf16 v[86:89], v[176:179], v[222:225], v[86:89]
	v_mfma_f32_16x16x32_bf16 v[78:81], v[150:153], v[226:229], v[78:81]
	v_mfma_f32_16x16x32_bf16 v[78:81], v[168:171], v[230:233], v[78:81]
	v_mfma_f32_16x16x32_bf16 v[70:73], v[172:175], v[226:229], v[70:73]
	v_mfma_f32_16x16x32_bf16 v[70:73], v[176:179], v[230:233], v[70:73]
	s_setprio 0
	s_setprio 1
	v_mfma_f32_16x16x32_bf16 v[122:125], v[186:189], v[202:205], v[122:125]
	v_mfma_f32_16x16x32_bf16 v[122:125], v[190:193], v[206:209], v[122:125]
	v_mfma_f32_16x16x32_bf16 v[114:117], v[194:197], v[202:205], v[114:117]
	v_mfma_f32_16x16x32_bf16 v[114:117], v[198:201], v[206:209], v[114:117]
	v_mfma_f32_16x16x32_bf16 v[106:109], v[186:189], v[210:213], v[106:109]
	v_mfma_f32_16x16x32_bf16 v[106:109], v[190:193], v[214:217], v[106:109]
	v_mfma_f32_16x16x32_bf16 v[98:101], v[194:197], v[210:213], v[98:101]
	v_mfma_f32_16x16x32_bf16 v[98:101], v[198:201], v[214:217], v[98:101]
	v_mfma_f32_16x16x32_bf16 v[90:93], v[186:189], v[218:221], v[90:93]
	v_mfma_f32_16x16x32_bf16 v[90:93], v[190:193], v[222:225], v[90:93]
	v_mfma_f32_16x16x32_bf16 v[82:85], v[194:197], v[218:221], v[82:85]
	v_mfma_f32_16x16x32_bf16 v[82:85], v[198:201], v[222:225], v[82:85]
	v_mfma_f32_16x16x32_bf16 v[74:77], v[186:189], v[226:229], v[74:77]
	v_mfma_f32_16x16x32_bf16 v[74:77], v[190:193], v[230:233], v[74:77]
	v_mfma_f32_16x16x32_bf16 v[66:69], v[194:197], v[226:229], v[66:69]
	v_mfma_f32_16x16x32_bf16 v[66:69], v[198:201], v[230:233], v[66:69]
	s_setprio 0
	s_barrier
	s_add_i32 s82, s68, s29
	s_add_u32 s98, s50, 0x80
	s_addc_u32 s99, s51, 0
	s_mov_b32 m0, s82
	ds_read_b128 v[202:205], v164 offset:16384
	ds_read_b128 v[206:209], v164 offset:17408
	ds_read_b128 v[210:213], v164 offset:18432
	ds_read_b128 v[214:217], v164 offset:19456
	ds_read_b128 v[218:221], v164 offset:20480
	ds_read_b128 v[222:225], v164 offset:21504
	ds_read_b128 v[226:229], v164 offset:22528
	ds_read_b128 v[230:233], v164 offset:23552
	global_load_lds_dwordx4 v134, s[50:51]
	s_add_i32 m0, s82, 0x2000
	s_add_u32 s82, s50, 0x100000
	s_addc_u32 s83, s51, 0
	s_add_i32 s84, s69, s29
	global_load_lds_dwordx4 v138, s[50:51]
	s_mov_b32 m0, s84
	global_load_lds_dwordx4 v134, s[82:83]
	s_add_i32 m0, s84, 0x2000
	s_nop 0
	global_load_lds_dwordx4 v138, s[82:83]
	s_add_u32 s100, s80, 0x80
	s_addc_u32 s101, s81, 0
	s_mov_b32 m0, s33
	s_nop 0
	global_load_lds_dwordx4 v132, s[80:81]
	s_mov_b32 m0, s35
	s_nop 0
	global_load_lds_dwordx4 v136, s[80:81]
	s_waitcnt vmcnt(8)
	s_waitcnt lgkmcnt(0)
	s_barrier
	s_setprio 1
	s_waitcnt lgkmcnt(0)
	v_mfma_f32_16x16x32_bf16 v[62:65], v[150:153], v[202:205], v[62:65]
	v_mfma_f32_16x16x32_bf16 v[62:65], v[168:171], v[206:209], v[62:65]
	v_mfma_f32_16x16x32_bf16 v[54:57], v[172:175], v[202:205], v[54:57]
	v_mfma_f32_16x16x32_bf16 v[54:57], v[176:179], v[206:209], v[54:57]
	v_mfma_f32_16x16x32_bf16 v[46:49], v[150:153], v[210:213], v[46:49]
	v_mfma_f32_16x16x32_bf16 v[46:49], v[168:171], v[214:217], v[46:49]
	v_mfma_f32_16x16x32_bf16 v[38:41], v[172:175], v[210:213], v[38:41]
	v_mfma_f32_16x16x32_bf16 v[38:41], v[176:179], v[214:217], v[38:41]
	v_mfma_f32_16x16x32_bf16 v[30:33], v[150:153], v[218:221], v[30:33]
	v_mfma_f32_16x16x32_bf16 v[30:33], v[168:171], v[222:225], v[30:33]
	v_mfma_f32_16x16x32_bf16 v[22:25], v[172:175], v[218:221], v[22:25]
	v_mfma_f32_16x16x32_bf16 v[22:25], v[176:179], v[222:225], v[22:25]
	v_mfma_f32_16x16x32_bf16 v[14:17], v[150:153], v[226:229], v[14:17]
	v_mfma_f32_16x16x32_bf16 v[14:17], v[168:171], v[230:233], v[14:17]
	v_mfma_f32_16x16x32_bf16 v[6:9], v[172:175], v[226:229], v[6:9]
	v_mfma_f32_16x16x32_bf16 v[6:9], v[176:179], v[230:233], v[6:9]
	s_setprio 0
	s_setprio 1
	v_mfma_f32_16x16x32_bf16 v[58:61], v[186:189], v[202:205], v[58:61]
	v_mfma_f32_16x16x32_bf16 v[58:61], v[190:193], v[206:209], v[58:61]
	v_mfma_f32_16x16x32_bf16 v[50:53], v[194:197], v[202:205], v[50:53]
	v_mfma_f32_16x16x32_bf16 v[50:53], v[198:201], v[206:209], v[50:53]
	v_mfma_f32_16x16x32_bf16 v[42:45], v[186:189], v[210:213], v[42:45]
	v_mfma_f32_16x16x32_bf16 v[42:45], v[190:193], v[214:217], v[42:45]
	v_mfma_f32_16x16x32_bf16 v[34:37], v[194:197], v[210:213], v[34:37]
	v_mfma_f32_16x16x32_bf16 v[34:37], v[198:201], v[214:217], v[34:37]
	v_mfma_f32_16x16x32_bf16 v[26:29], v[186:189], v[218:221], v[26:29]
	v_mfma_f32_16x16x32_bf16 v[26:29], v[190:193], v[222:225], v[26:29]
	v_mfma_f32_16x16x32_bf16 v[18:21], v[194:197], v[218:221], v[18:21]
	v_mfma_f32_16x16x32_bf16 v[18:21], v[198:201], v[222:225], v[18:21]
	v_mfma_f32_16x16x32_bf16 v[10:13], v[186:189], v[226:229], v[10:13]
	v_mfma_f32_16x16x32_bf16 v[10:13], v[190:193], v[230:233], v[10:13]
	v_mfma_f32_16x16x32_bf16 v[2:5], v[194:197], v[226:229], v[2:5]
	v_mfma_f32_16x16x32_bf16 v[2:5], v[198:201], v[230:233], v[2:5]
	s_setprio 0
	s_barrier
	s_add_i32 s82, 0, 0x18000
	v_add_u32_e32 v140, s82, v158
	s_add_i32 s83, 0, 0x1c000
	ds_read_b128 v[150:153], v140
	ds_read_b128 v[168:171], v140 offset:1024
	ds_read_b128 v[172:175], v140 offset:2048
	ds_read_b128 v[176:179], v140 offset:3072
	v_add_u32_e32 v140, s83, v158
	ds_read_b128 v[186:189], v140
	ds_read_b128 v[190:193], v140 offset:1024
	ds_read_b128 v[194:197], v140 offset:2048
	ds_read_b128 v[198:201], v140 offset:3072
	s_add_u32 s80, s80, 0x100000
	s_addc_u32 s81, s81, 0
	s_mov_b32 m0, s59
	ds_read_b128 v[202:205], v164 offset:32768
	ds_read_b128 v[206:209], v164 offset:33792
	ds_read_b128 v[210:213], v164 offset:34816
	ds_read_b128 v[214:217], v164 offset:35840
	ds_read_b128 v[218:221], v164 offset:36864
	ds_read_b128 v[222:225], v164 offset:37888
	ds_read_b128 v[226:229], v164 offset:38912
	ds_read_b128 v[230:233], v164 offset:39936
	global_load_lds_dwordx4 v132, s[80:81]
	s_mov_b32 m0, s62
	s_nop 0
	global_load_lds_dwordx4 v136, s[80:81]
	s_waitcnt vmcnt(8)
	s_waitcnt lgkmcnt(0)
	s_barrier
	s_setprio 1
	s_waitcnt lgkmcnt(0)
	v_mfma_f32_16x16x32_bf16 v[126:129], v[150:153], v[202:205], v[126:129]
	v_mfma_f32_16x16x32_bf16 v[126:129], v[168:171], v[206:209], v[126:129]
	v_mfma_f32_16x16x32_bf16 v[118:121], v[172:175], v[202:205], v[118:121]
	v_mfma_f32_16x16x32_bf16 v[118:121], v[176:179], v[206:209], v[118:121]
	v_mfma_f32_16x16x32_bf16 v[110:113], v[150:153], v[210:213], v[110:113]
	v_mfma_f32_16x16x32_bf16 v[110:113], v[168:171], v[214:217], v[110:113]
	v_mfma_f32_16x16x32_bf16 v[102:105], v[172:175], v[210:213], v[102:105]
	v_mfma_f32_16x16x32_bf16 v[102:105], v[176:179], v[214:217], v[102:105]
	v_mfma_f32_16x16x32_bf16 v[94:97], v[150:153], v[218:221], v[94:97]
	v_mfma_f32_16x16x32_bf16 v[94:97], v[168:171], v[222:225], v[94:97]
	v_mfma_f32_16x16x32_bf16 v[86:89], v[172:175], v[218:221], v[86:89]
	v_mfma_f32_16x16x32_bf16 v[86:89], v[176:179], v[222:225], v[86:89]
	v_mfma_f32_16x16x32_bf16 v[78:81], v[150:153], v[226:229], v[78:81]
	v_mfma_f32_16x16x32_bf16 v[78:81], v[168:171], v[230:233], v[78:81]
	v_mfma_f32_16x16x32_bf16 v[70:73], v[172:175], v[226:229], v[70:73]
	v_mfma_f32_16x16x32_bf16 v[70:73], v[176:179], v[230:233], v[70:73]
	s_setprio 0
	s_setprio 1
	v_mfma_f32_16x16x32_bf16 v[122:125], v[186:189], v[202:205], v[122:125]
	v_mfma_f32_16x16x32_bf16 v[122:125], v[190:193], v[206:209], v[122:125]
	v_mfma_f32_16x16x32_bf16 v[114:117], v[194:197], v[202:205], v[114:117]
	v_mfma_f32_16x16x32_bf16 v[114:117], v[198:201], v[206:209], v[114:117]
	v_mfma_f32_16x16x32_bf16 v[106:109], v[186:189], v[210:213], v[106:109]
	v_mfma_f32_16x16x32_bf16 v[106:109], v[190:193], v[214:217], v[106:109]
	v_mfma_f32_16x16x32_bf16 v[98:101], v[194:197], v[210:213], v[98:101]
	v_mfma_f32_16x16x32_bf16 v[98:101], v[198:201], v[214:217], v[98:101]
	v_mfma_f32_16x16x32_bf16 v[90:93], v[186:189], v[218:221], v[90:93]
	v_mfma_f32_16x16x32_bf16 v[90:93], v[190:193], v[222:225], v[90:93]
	v_mfma_f32_16x16x32_bf16 v[82:85], v[194:197], v[218:221], v[82:85]
	v_mfma_f32_16x16x32_bf16 v[82:85], v[198:201], v[222:225], v[82:85]
	v_mfma_f32_16x16x32_bf16 v[74:77], v[186:189], v[226:229], v[74:77]
	v_mfma_f32_16x16x32_bf16 v[74:77], v[190:193], v[230:233], v[74:77]
	v_mfma_f32_16x16x32_bf16 v[66:69], v[194:197], v[226:229], v[66:69]
	v_mfma_f32_16x16x32_bf16 v[66:69], v[198:201], v[230:233], v[66:69]
	s_setprio 0
	s_barrier
	s_add_i32 s80, s82, s29
	s_mov_b32 m0, s80
	ds_read_b128 v[202:205], v164 offset:49152
	ds_read_b128 v[206:209], v164 offset:50176
	ds_read_b128 v[210:213], v164 offset:51200
	ds_read_b128 v[214:217], v164 offset:52224
	ds_read_b128 v[218:221], v164 offset:53248
	ds_read_b128 v[222:225], v164 offset:54272
	ds_read_b128 v[226:229], v164 offset:55296
	ds_read_b128 v[230:233], v164 offset:56320
	global_load_lds_dwordx4 v134, s[98:99]
	s_add_i32 m0, s80, 0x2000
	s_add_u32 s50, s50, 0x100080
	s_addc_u32 s51, s51, 0
	s_add_i32 s80, s83, s29
	global_load_lds_dwordx4 v138, s[98:99]
	s_mov_b32 m0, s80
	s_nop 0
	global_load_lds_dwordx4 v134, s[50:51]
	s_add_i32 m0, s80, 0x2000
	s_nop 0
	global_load_lds_dwordx4 v138, s[50:51]
	s_mov_b32 m0, s65
	s_nop 0
	global_load_lds_dwordx4 v132, s[100:101]
	s_mov_b32 m0, s66
	s_nop 0
	global_load_lds_dwordx4 v136, s[100:101]
	s_waitcnt vmcnt(8)
	s_waitcnt lgkmcnt(0)
	s_barrier
	s_setprio 1
	s_waitcnt lgkmcnt(0)
	v_mfma_f32_16x16x32_bf16 v[62:65], v[150:153], v[202:205], v[62:65]
	v_mfma_f32_16x16x32_bf16 v[62:65], v[168:171], v[206:209], v[62:65]
	v_mfma_f32_16x16x32_bf16 v[54:57], v[172:175], v[202:205], v[54:57]
	v_mfma_f32_16x16x32_bf16 v[54:57], v[176:179], v[206:209], v[54:57]
	v_mfma_f32_16x16x32_bf16 v[46:49], v[150:153], v[210:213], v[46:49]
	v_mfma_f32_16x16x32_bf16 v[46:49], v[168:171], v[214:217], v[46:49]
	v_mfma_f32_16x16x32_bf16 v[38:41], v[172:175], v[210:213], v[38:41]
	v_mfma_f32_16x16x32_bf16 v[38:41], v[176:179], v[214:217], v[38:41]
	v_mfma_f32_16x16x32_bf16 v[30:33], v[150:153], v[218:221], v[30:33]
	v_mfma_f32_16x16x32_bf16 v[30:33], v[168:171], v[222:225], v[30:33]
	v_mfma_f32_16x16x32_bf16 v[22:25], v[172:175], v[218:221], v[22:25]
	v_mfma_f32_16x16x32_bf16 v[22:25], v[176:179], v[222:225], v[22:25]
	v_mfma_f32_16x16x32_bf16 v[14:17], v[150:153], v[226:229], v[14:17]
	v_mfma_f32_16x16x32_bf16 v[14:17], v[168:171], v[230:233], v[14:17]
	v_mfma_f32_16x16x32_bf16 v[6:9], v[172:175], v[226:229], v[6:9]
	v_mfma_f32_16x16x32_bf16 v[6:9], v[176:179], v[230:233], v[6:9]
	s_setprio 0
	s_setprio 1
	v_mfma_f32_16x16x32_bf16 v[58:61], v[186:189], v[202:205], v[58:61]
	v_mfma_f32_16x16x32_bf16 v[58:61], v[190:193], v[206:209], v[58:61]
	v_mfma_f32_16x16x32_bf16 v[50:53], v[194:197], v[202:205], v[50:53]
	v_mfma_f32_16x16x32_bf16 v[50:53], v[198:201], v[206:209], v[50:53]
	v_mfma_f32_16x16x32_bf16 v[42:45], v[186:189], v[210:213], v[42:45]
	v_mfma_f32_16x16x32_bf16 v[42:45], v[190:193], v[214:217], v[42:45]
	v_mfma_f32_16x16x32_bf16 v[34:37], v[194:197], v[210:213], v[34:37]
	v_mfma_f32_16x16x32_bf16 v[34:37], v[198:201], v[214:217], v[34:37]
	v_mfma_f32_16x16x32_bf16 v[26:29], v[186:189], v[218:221], v[26:29]
	v_mfma_f32_16x16x32_bf16 v[26:29], v[190:193], v[222:225], v[26:29]
	v_mfma_f32_16x16x32_bf16 v[18:21], v[194:197], v[218:221], v[18:21]
	v_mfma_f32_16x16x32_bf16 v[18:21], v[198:201], v[222:225], v[18:21]
	v_mfma_f32_16x16x32_bf16 v[10:13], v[186:189], v[226:229], v[10:13]
	v_mfma_f32_16x16x32_bf16 v[10:13], v[190:193], v[230:233], v[10:13]
	v_mfma_f32_16x16x32_bf16 v[2:5], v[194:197], v[226:229], v[2:5]
	v_mfma_f32_16x16x32_bf16 v[2:5], v[198:201], v[230:233], v[2:5]
	s_setprio 0
	s_barrier
	s_add_i32 s79, s79, 2
	s_add_u32 s6, s6, 0x100
	s_addc_u32 s7, s7, 0
	s_add_u32 s77, s77, 0x100
	s_addc_u32 s78, s78, 0
	s_cmp_gt_u32 s79, 61
	s_cbranch_scc0 .LBB0_2212
	s_and_b64 vcc, exec, s[40:41]
	s_cbranch_vccz .LBB0_2215
	s_barrier

.LBB0_2340:
	ds_read_b128 v[130:133], v163
	ds_read_b128 v[134:137], v163 offset:1024
	ds_read_b128 v[138:141], v163 offset:2048
	ds_read_b128 v[142:145], v163 offset:3072
	ds_read_b128 v[146:149], v190
	ds_read_b128 v[150:153], v190 offset:1024
	ds_read_b128 v[174:177], v190 offset:2048
	ds_read_b128 v[178:181], v190 offset:3072
	s_add_u32 s42, s40, 0xffd50080
	s_addc_u32 s43, s41, -1
	s_cmpk_eq_i32 s71, 0xa8
	s_cselect_b32 s45, s1, s43
	s_cselect_b32 s44, s0, s42
	s_cselect_b32 s43, s39, s70
	s_cselect_b32 s42, s38, s12
	s_add_i32 m0, s46, 0xc000
	ds_read_b128 v[186:189], v191
	ds_read_b128 v[194:197], v191 offset:1024
	ds_read_b128 v[198:201], v191 offset:2048
	ds_read_b128 v[202:205], v191 offset:3072
	ds_read_b128 v[206:209], v191 offset:4096
	ds_read_b128 v[210:213], v191 offset:5120
	ds_read_b128 v[214:217], v191 offset:6144
	ds_read_b128 v[218:221], v191 offset:7168
	global_load_lds_dwordx4 v166, s[40:41]
	s_add_i32 m0, s46, 0xe000
	s_nop 0
	global_load_lds_dwordx4 v168, s[40:41]
	s_waitcnt vmcnt(8)
	s_waitcnt lgkmcnt(0)
	s_barrier
	s_setprio 1
	s_waitcnt lgkmcnt(0)
	v_mfma_f32_16x16x32_bf16 v[126:129], v[130:133], v[186:189], v[126:129]
	v_mfma_f32_16x16x32_bf16 v[126:129], v[134:137], v[194:197], v[126:129]
	v_mfma_f32_16x16x32_bf16 v[122:125], v[138:141], v[186:189], v[122:125]
	v_mfma_f32_16x16x32_bf16 v[122:125], v[142:145], v[194:197], v[122:125]
	v_mfma_f32_16x16x32_bf16 v[110:113], v[130:133], v[198:201], v[110:113]
	v_mfma_f32_16x16x32_bf16 v[110:113], v[134:137], v[202:205], v[110:113]
	v_mfma_f32_16x16x32_bf16 v[106:109], v[138:141], v[198:201], v[106:109]
	v_mfma_f32_16x16x32_bf16 v[106:109], v[142:145], v[202:205], v[106:109]
	v_mfma_f32_16x16x32_bf16 v[94:97], v[130:133], v[206:209], v[94:97]
	v_mfma_f32_16x16x32_bf16 v[94:97], v[134:137], v[210:213], v[94:97]
	v_mfma_f32_16x16x32_bf16 v[90:93], v[138:141], v[206:209], v[90:93]
	v_mfma_f32_16x16x32_bf16 v[90:93], v[142:145], v[210:213], v[90:93]
	v_mfma_f32_16x16x32_bf16 v[78:81], v[130:133], v[214:217], v[78:81]
	v_mfma_f32_16x16x32_bf16 v[78:81], v[134:137], v[218:221], v[78:81]
	v_mfma_f32_16x16x32_bf16 v[74:77], v[138:141], v[214:217], v[74:77]
	v_mfma_f32_16x16x32_bf16 v[74:77], v[142:145], v[218:221], v[74:77]
	s_setprio 0
	s_setprio 1
	v_mfma_f32_16x16x32_bf16 v[118:121], v[146:149], v[186:189], v[118:121]
	v_mfma_f32_16x16x32_bf16 v[118:121], v[150:153], v[194:197], v[118:121]
	v_mfma_f32_16x16x32_bf16 v[114:117], v[174:177], v[186:189], v[114:117]
	v_mfma_f32_16x16x32_bf16 v[114:117], v[178:181], v[194:197], v[114:117]
	v_mfma_f32_16x16x32_bf16 v[102:105], v[146:149], v[198:201], v[102:105]
	v_mfma_f32_16x16x32_bf16 v[102:105], v[150:153], v[202:205], v[102:105]
	v_mfma_f32_16x16x32_bf16 v[98:101], v[174:177], v[198:201], v[98:101]
	v_mfma_f32_16x16x32_bf16 v[98:101], v[178:181], v[202:205], v[98:101]
	v_mfma_f32_16x16x32_bf16 v[86:89], v[146:149], v[206:209], v[86:89]
	v_mfma_f32_16x16x32_bf16 v[86:89], v[150:153], v[210:213], v[86:89]
	v_mfma_f32_16x16x32_bf16 v[82:85], v[174:177], v[206:209], v[82:85]
	v_mfma_f32_16x16x32_bf16 v[82:85], v[178:181], v[210:213], v[82:85]
	v_mfma_f32_16x16x32_bf16 v[70:73], v[146:149], v[214:217], v[70:73]
	v_mfma_f32_16x16x32_bf16 v[70:73], v[150:153], v[218:221], v[70:73]
	v_mfma_f32_16x16x32_bf16 v[66:69], v[174:177], v[214:217], v[66:69]
	v_mfma_f32_16x16x32_bf16 v[66:69], v[178:181], v[218:221], v[66:69]
	s_setprio 0
	s_barrier
	s_add_i32 s72, s65, s35
	s_add_u32 s98, s42, 0x80
	s_addc_u32 s99, s43, 0
	s_mov_b32 m0, s72
	ds_read_b128 v[186:189], v191 offset:16384
	ds_read_b128 v[194:197], v191 offset:17408
	ds_read_b128 v[198:201], v191 offset:18432
	ds_read_b128 v[202:205], v191 offset:19456
	ds_read_b128 v[206:209], v191 offset:20480
	ds_read_b128 v[210:213], v191 offset:21504
	ds_read_b128 v[214:217], v191 offset:22528
	ds_read_b128 v[218:221], v191 offset:23552
	global_load_lds_dwordx4 v156, s[42:43]
	s_add_i32 m0, s72, 0x2000
	s_add_u32 s72, s42, 0x2b0000
	s_addc_u32 s73, s43, 0
	s_add_i32 s74, s66, s35
	global_load_lds_dwordx4 v160, s[42:43]
	s_mov_b32 m0, s74
	global_load_lds_dwordx4 v156, s[72:73]
	s_add_i32 m0, s74, 0x2000
	s_nop 0
	global_load_lds_dwordx4 v160, s[72:73]
	s_add_u32 s100, s44, 0x80
	s_addc_u32 s101, s45, 0
	s_mov_b32 m0, s46
	s_nop 0
	global_load_lds_dwordx4 v154, s[44:45]
	s_mov_b32 m0, s47
	s_nop 0
	global_load_lds_dwordx4 v158, s[44:45]
	s_waitcnt vmcnt(8)
	s_waitcnt lgkmcnt(0)
	s_barrier
	s_setprio 1
	s_waitcnt lgkmcnt(0)
	v_mfma_f32_16x16x32_bf16 v[62:65], v[130:133], v[186:189], v[62:65]
	v_mfma_f32_16x16x32_bf16 v[62:65], v[134:137], v[194:197], v[62:65]
	v_mfma_f32_16x16x32_bf16 v[58:61], v[138:141], v[186:189], v[58:61]
	v_mfma_f32_16x16x32_bf16 v[58:61], v[142:145], v[194:197], v[58:61]
	v_mfma_f32_16x16x32_bf16 v[46:49], v[130:133], v[198:201], v[46:49]
	v_mfma_f32_16x16x32_bf16 v[46:49], v[134:137], v[202:205], v[46:49]
	v_mfma_f32_16x16x32_bf16 v[42:45], v[138:141], v[198:201], v[42:45]
	v_mfma_f32_16x16x32_bf16 v[42:45], v[142:145], v[202:205], v[42:45]
	v_mfma_f32_16x16x32_bf16 v[30:33], v[130:133], v[206:209], v[30:33]
	v_mfma_f32_16x16x32_bf16 v[30:33], v[134:137], v[210:213], v[30:33]
	v_mfma_f32_16x16x32_bf16 v[26:29], v[138:141], v[206:209], v[26:29]
	v_mfma_f32_16x16x32_bf16 v[26:29], v[142:145], v[210:213], v[26:29]
	v_mfma_f32_16x16x32_bf16 v[14:17], v[130:133], v[214:217], v[14:17]
	v_mfma_f32_16x16x32_bf16 v[14:17], v[134:137], v[218:221], v[14:17]
	v_mfma_f32_16x16x32_bf16 v[10:13], v[138:141], v[214:217], v[10:13]
	v_mfma_f32_16x16x32_bf16 v[10:13], v[142:145], v[218:221], v[10:13]
	s_setprio 0
	s_setprio 1
	v_mfma_f32_16x16x32_bf16 v[54:57], v[146:149], v[186:189], v[54:57]
	v_mfma_f32_16x16x32_bf16 v[54:57], v[150:153], v[194:197], v[54:57]
	v_mfma_f32_16x16x32_bf16 v[50:53], v[174:177], v[186:189], v[50:53]
	v_mfma_f32_16x16x32_bf16 v[50:53], v[178:181], v[194:197], v[50:53]
	v_mfma_f32_16x16x32_bf16 v[38:41], v[146:149], v[198:201], v[38:41]
	v_mfma_f32_16x16x32_bf16 v[38:41], v[150:153], v[202:205], v[38:41]
	v_mfma_f32_16x16x32_bf16 v[34:37], v[174:177], v[198:201], v[34:37]
	v_mfma_f32_16x16x32_bf16 v[34:37], v[178:181], v[202:205], v[34:37]
	v_mfma_f32_16x16x32_bf16 v[22:25], v[146:149], v[206:209], v[22:25]
	v_mfma_f32_16x16x32_bf16 v[22:25], v[150:153], v[210:213], v[22:25]
	v_mfma_f32_16x16x32_bf16 v[18:21], v[174:177], v[206:209], v[18:21]
	v_mfma_f32_16x16x32_bf16 v[18:21], v[178:181], v[210:213], v[18:21]
	v_mfma_f32_16x16x32_bf16 v[6:9], v[146:149], v[214:217], v[6:9]
	v_mfma_f32_16x16x32_bf16 v[6:9], v[150:153], v[218:221], v[6:9]
	v_mfma_f32_16x16x32_bf16 v[2:5], v[174:177], v[214:217], v[2:5]
	v_mfma_f32_16x16x32_bf16 v[2:5], v[178:181], v[218:221], v[2:5]
	s_setprio 0
	s_barrier
	s_add_i32 s72, 0, 0x18000
	s_add_i32 s73, 0, 0x1c000
	v_add_u32_e32 v142, s72, v183
	v_add_u32_e32 v178, s73, v183
	ds_read_b128 v[130:133], v142
	ds_read_b128 v[134:137], v142 offset:1024
	ds_read_b128 v[138:141], v142 offset:2048
	ds_read_b128 v[142:145], v142 offset:3072
	ds_read_b128 v[146:149], v178
	ds_read_b128 v[150:153], v178 offset:1024
	ds_read_b128 v[174:177], v178 offset:2048
	ds_read_b128 v[178:181], v178 offset:3072
	s_add_u32 s44, s44, 0x2b0000
	s_addc_u32 s45, s45, 0
	s_mov_b32 m0, s48
	ds_read_b128 v[186:189], v191 offset:32768
	ds_read_b128 v[194:197], v191 offset:33792
	ds_read_b128 v[198:201], v191 offset:34816
	ds_read_b128 v[202:205], v191 offset:35840
	ds_read_b128 v[206:209], v191 offset:36864
	ds_read_b128 v[210:213], v191 offset:37888
	ds_read_b128 v[214:217], v191 offset:38912
	ds_read_b128 v[218:221], v191 offset:39936
	global_load_lds_dwordx4 v154, s[44:45]
	s_mov_b32 m0, s49
	s_nop 0
	global_load_lds_dwordx4 v158, s[44:45]
	s_waitcnt vmcnt(8)
	s_waitcnt lgkmcnt(0)
	s_barrier
	s_setprio 1
	s_waitcnt lgkmcnt(0)
	v_mfma_f32_16x16x32_bf16 v[126:129], v[130:133], v[186:189], v[126:129]
	v_mfma_f32_16x16x32_bf16 v[126:129], v[134:137], v[194:197], v[126:129]
	v_mfma_f32_16x16x32_bf16 v[122:125], v[138:141], v[186:189], v[122:125]
	v_mfma_f32_16x16x32_bf16 v[122:125], v[142:145], v[194:197], v[122:125]
	v_mfma_f32_16x16x32_bf16 v[110:113], v[130:133], v[198:201], v[110:113]
	v_mfma_f32_16x16x32_bf16 v[110:113], v[134:137], v[202:205], v[110:113]
	v_mfma_f32_16x16x32_bf16 v[106:109], v[138:141], v[198:201], v[106:109]
	v_mfma_f32_16x16x32_bf16 v[106:109], v[142:145], v[202:205], v[106:109]
	v_mfma_f32_16x16x32_bf16 v[94:97], v[130:133], v[206:209], v[94:97]
	v_mfma_f32_16x16x32_bf16 v[94:97], v[134:137], v[210:213], v[94:97]
	v_mfma_f32_16x16x32_bf16 v[90:93], v[138:141], v[206:209], v[90:93]
	v_mfma_f32_16x16x32_bf16 v[90:93], v[142:145], v[210:213], v[90:93]
	v_mfma_f32_16x16x32_bf16 v[78:81], v[130:133], v[214:217], v[78:81]
	v_mfma_f32_16x16x32_bf16 v[78:81], v[134:137], v[218:221], v[78:81]
	v_mfma_f32_16x16x32_bf16 v[74:77], v[138:141], v[214:217], v[74:77]
	v_mfma_f32_16x16x32_bf16 v[74:77], v[142:145], v[218:221], v[74:77]
	s_setprio 0
	s_setprio 1
	v_mfma_f32_16x16x32_bf16 v[118:121], v[146:149], v[186:189], v[118:121]
	v_mfma_f32_16x16x32_bf16 v[118:121], v[150:153], v[194:197], v[118:121]
	v_mfma_f32_16x16x32_bf16 v[114:117], v[174:177], v[186:189], v[114:117]
	v_mfma_f32_16x16x32_bf16 v[114:117], v[178:181], v[194:197], v[114:117]
	v_mfma_f32_16x16x32_bf16 v[102:105], v[146:149], v[198:201], v[102:105]
	v_mfma_f32_16x16x32_bf16 v[102:105], v[150:153], v[202:205], v[102:105]
	v_mfma_f32_16x16x32_bf16 v[98:101], v[174:177], v[198:201], v[98:101]
	v_mfma_f32_16x16x32_bf16 v[98:101], v[178:181], v[202:205], v[98:101]
	v_mfma_f32_16x16x32_bf16 v[86:89], v[146:149], v[206:209], v[86:89]
	v_mfma_f32_16x16x32_bf16 v[86:89], v[150:153], v[210:213], v[86:89]
	v_mfma_f32_16x16x32_bf16 v[82:85], v[174:177], v[206:209], v[82:85]
	v_mfma_f32_16x16x32_bf16 v[82:85], v[178:181], v[210:213], v[82:85]
	v_mfma_f32_16x16x32_bf16 v[70:73], v[146:149], v[214:217], v[70:73]
	v_mfma_f32_16x16x32_bf16 v[70:73], v[150:153], v[218:221], v[70:73]
	v_mfma_f32_16x16x32_bf16 v[66:69], v[174:177], v[214:217], v[66:69]
	v_mfma_f32_16x16x32_bf16 v[66:69], v[178:181], v[218:221], v[66:69]
	s_setprio 0
	s_barrier
	s_add_i32 s44, s72, s35
	s_mov_b32 m0, s44
	ds_read_b128 v[186:189], v191 offset:49152
	ds_read_b128 v[194:197], v191 offset:50176
	ds_read_b128 v[198:201], v191 offset:51200
	ds_read_b128 v[202:205], v191 offset:52224
	ds_read_b128 v[206:209], v191 offset:53248
	ds_read_b128 v[210:213], v191 offset:54272
	ds_read_b128 v[214:217], v191 offset:55296
	ds_read_b128 v[218:221], v191 offset:56320
	global_load_lds_dwordx4 v156, s[98:99]
	s_add_i32 m0, s44, 0x2000
	s_add_u32 s42, s42, 0x2b0080
	s_addc_u32 s43, s43, 0
	s_add_i32 s44, s73, s35
	global_load_lds_dwordx4 v160, s[98:99]
	s_mov_b32 m0, s44
	s_nop 0
	global_load_lds_dwordx4 v156, s[42:43]
	s_add_i32 m0, s44, 0x2000
	s_nop 0
	global_load_lds_dwordx4 v160, s[42:43]
	s_mov_b32 m0, s51
	s_nop 0
	global_load_lds_dwordx4 v154, s[100:101]
	s_mov_b32 m0, s59
	s_nop 0
	global_load_lds_dwordx4 v158, s[100:101]
	s_waitcnt vmcnt(8)
	s_waitcnt lgkmcnt(0)
	s_barrier
	s_setprio 1
	s_waitcnt lgkmcnt(0)
	v_mfma_f32_16x16x32_bf16 v[62:65], v[130:133], v[186:189], v[62:65]
	v_mfma_f32_16x16x32_bf16 v[62:65], v[134:137], v[194:197], v[62:65]
	v_mfma_f32_16x16x32_bf16 v[58:61], v[138:141], v[186:189], v[58:61]
	v_mfma_f32_16x16x32_bf16 v[58:61], v[142:145], v[194:197], v[58:61]
	v_mfma_f32_16x16x32_bf16 v[46:49], v[130:133], v[198:201], v[46:49]
	v_mfma_f32_16x16x32_bf16 v[46:49], v[134:137], v[202:205], v[46:49]
	v_mfma_f32_16x16x32_bf16 v[42:45], v[138:141], v[198:201], v[42:45]
	v_mfma_f32_16x16x32_bf16 v[42:45], v[142:145], v[202:205], v[42:45]
	v_mfma_f32_16x16x32_bf16 v[30:33], v[130:133], v[206:209], v[30:33]
	v_mfma_f32_16x16x32_bf16 v[30:33], v[134:137], v[210:213], v[30:33]
	v_mfma_f32_16x16x32_bf16 v[26:29], v[138:141], v[206:209], v[26:29]
	v_mfma_f32_16x16x32_bf16 v[26:29], v[142:145], v[210:213], v[26:29]
	v_mfma_f32_16x16x32_bf16 v[14:17], v[130:133], v[214:217], v[14:17]
	v_mfma_f32_16x16x32_bf16 v[14:17], v[134:137], v[218:221], v[14:17]
	v_mfma_f32_16x16x32_bf16 v[10:13], v[138:141], v[214:217], v[10:13]
	v_mfma_f32_16x16x32_bf16 v[10:13], v[142:145], v[218:221], v[10:13]
	s_setprio 0
	s_setprio 1
	v_mfma_f32_16x16x32_bf16 v[54:57], v[146:149], v[186:189], v[54:57]
	v_mfma_f32_16x16x32_bf16 v[54:57], v[150:153], v[194:197], v[54:57]
	v_mfma_f32_16x16x32_bf16 v[50:53], v[174:177], v[186:189], v[50:53]
	v_mfma_f32_16x16x32_bf16 v[50:53], v[178:181], v[194:197], v[50:53]
	v_mfma_f32_16x16x32_bf16 v[38:41], v[146:149], v[198:201], v[38:41]
	v_mfma_f32_16x16x32_bf16 v[38:41], v[150:153], v[202:205], v[38:41]
	v_mfma_f32_16x16x32_bf16 v[34:37], v[174:177], v[198:201], v[34:37]
	v_mfma_f32_16x16x32_bf16 v[34:37], v[178:181], v[202:205], v[34:37]
	v_mfma_f32_16x16x32_bf16 v[22:25], v[146:149], v[206:209], v[22:25]
	v_mfma_f32_16x16x32_bf16 v[22:25], v[150:153], v[210:213], v[22:25]
	v_mfma_f32_16x16x32_bf16 v[18:21], v[174:177], v[206:209], v[18:21]
	v_mfma_f32_16x16x32_bf16 v[18:21], v[178:181], v[210:213], v[18:21]
	v_mfma_f32_16x16x32_bf16 v[6:9], v[146:149], v[214:217], v[6:9]
	v_mfma_f32_16x16x32_bf16 v[6:9], v[150:153], v[218:221], v[6:9]
	v_mfma_f32_16x16x32_bf16 v[2:5], v[174:177], v[214:217], v[2:5]
	v_mfma_f32_16x16x32_bf16 v[2:5], v[178:181], v[218:221], v[2:5]
	s_setprio 0
	s_barrier
	s_add_i32 s71, s71, 2
	s_add_u32 s40, s40, 0x100
	s_addc_u32 s41, s41, 0
	s_add_u32 s12, s12, 0x100
	s_addc_u32 s70, s70, 0
	s_cmpk_gt_u32 s71, 0xa9
	s_cbranch_scc0 .LBB0_2340
	s_and_b64 vcc, exec, s[36:37]
	s_cbranch_vccz .LBB0_2343
	s_barrier

.LBB0_2464:
	ds_read_b128 v[150:153], v167
	ds_read_b128 v[172:175], v167 offset:1024
	ds_read_b128 v[176:179], v167 offset:2048
	ds_read_b128 v[184:187], v167 offset:3072
	ds_read_b128 v[188:191], v168
	ds_read_b128 v[192:195], v168 offset:1024
	ds_read_b128 v[196:199], v168 offset:2048
	ds_read_b128 v[200:203], v168 offset:3072
	s_add_u32 s74, s6, 0xfff00080
	s_addc_u32 s75, s7, -1
	s_cmp_eq_u32 s87, 60
	s_cselect_b32 s77, s47, s75
	s_cselect_b32 s76, s83, s74
	s_cselect_b32 s75, s45, s86
	s_cselect_b32 s74, s84, s85
	s_add_i32 m0, s59, 0xc000
	ds_read_b128 v[204:207], v169
	ds_read_b128 v[208:211], v169 offset:1024
	ds_read_b128 v[212:215], v169 offset:2048
	ds_read_b128 v[216:219], v169 offset:3072
	ds_read_b128 v[220:223], v169 offset:4096
	ds_read_b128 v[224:227], v169 offset:5120
	ds_read_b128 v[228:231], v169 offset:6144
	ds_read_b128 v[232:235], v169 offset:7168
	global_load_lds_dwordx4 v142, s[6:7]
	s_add_i32 m0, s59, 0xe000
	s_nop 0
	global_load_lds_dwordx4 v144, s[6:7]
	s_waitcnt vmcnt(8)
	s_waitcnt lgkmcnt(0)
	s_barrier
	s_setprio 1
	s_waitcnt lgkmcnt(0)
	v_mfma_f32_16x16x32_bf16 v[126:129], v[150:153], v[204:207], v[126:129]
	v_mfma_f32_16x16x32_bf16 v[126:129], v[172:175], v[208:211], v[126:129]
	v_mfma_f32_16x16x32_bf16 v[122:125], v[176:179], v[204:207], v[122:125]
	v_mfma_f32_16x16x32_bf16 v[122:125], v[184:187], v[208:211], v[122:125]
	v_mfma_f32_16x16x32_bf16 v[110:113], v[150:153], v[212:215], v[110:113]
	v_mfma_f32_16x16x32_bf16 v[110:113], v[172:175], v[216:219], v[110:113]
	v_mfma_f32_16x16x32_bf16 v[106:109], v[176:179], v[212:215], v[106:109]
	v_mfma_f32_16x16x32_bf16 v[106:109], v[184:187], v[216:219], v[106:109]
	v_mfma_f32_16x16x32_bf16 v[94:97], v[150:153], v[220:223], v[94:97]
	v_mfma_f32_16x16x32_bf16 v[94:97], v[172:175], v[224:227], v[94:97]
	v_mfma_f32_16x16x32_bf16 v[90:93], v[176:179], v[220:223], v[90:93]
	v_mfma_f32_16x16x32_bf16 v[90:93], v[184:187], v[224:227], v[90:93]
	v_mfma_f32_16x16x32_bf16 v[78:81], v[150:153], v[228:231], v[78:81]
	v_mfma_f32_16x16x32_bf16 v[78:81], v[172:175], v[232:235], v[78:81]
	v_mfma_f32_16x16x32_bf16 v[74:77], v[176:179], v[228:231], v[74:77]
	v_mfma_f32_16x16x32_bf16 v[74:77], v[184:187], v[232:235], v[74:77]
	s_setprio 0
	s_setprio 1
	v_mfma_f32_16x16x32_bf16 v[118:121], v[188:191], v[204:207], v[118:121]
	v_mfma_f32_16x16x32_bf16 v[118:121], v[192:195], v[208:211], v[118:121]
	v_mfma_f32_16x16x32_bf16 v[114:117], v[196:199], v[204:207], v[114:117]
	v_mfma_f32_16x16x32_bf16 v[114:117], v[200:203], v[208:211], v[114:117]
	v_mfma_f32_16x16x32_bf16 v[102:105], v[188:191], v[212:215], v[102:105]
	v_mfma_f32_16x16x32_bf16 v[102:105], v[192:195], v[216:219], v[102:105]
	v_mfma_f32_16x16x32_bf16 v[98:101], v[196:199], v[212:215], v[98:101]
	v_mfma_f32_16x16x32_bf16 v[98:101], v[200:203], v[216:219], v[98:101]
	v_mfma_f32_16x16x32_bf16 v[86:89], v[188:191], v[220:223], v[86:89]
	v_mfma_f32_16x16x32_bf16 v[86:89], v[192:195], v[224:227], v[86:89]
	v_mfma_f32_16x16x32_bf16 v[82:85], v[196:199], v[220:223], v[82:85]
	v_mfma_f32_16x16x32_bf16 v[82:85], v[200:203], v[224:227], v[82:85]
	v_mfma_f32_16x16x32_bf16 v[70:73], v[188:191], v[228:231], v[70:73]
	v_mfma_f32_16x16x32_bf16 v[70:73], v[192:195], v[232:235], v[70:73]
	v_mfma_f32_16x16x32_bf16 v[66:69], v[196:199], v[228:231], v[66:69]
	v_mfma_f32_16x16x32_bf16 v[66:69], v[200:203], v[232:235], v[66:69]
	s_setprio 0
	s_barrier
	s_add_i32 s88, s70, s27
	s_add_u32 s98, s74, 0x80
	s_addc_u32 s99, s75, 0
	s_mov_b32 m0, s88
	ds_read_b128 v[204:207], v169 offset:16384
	ds_read_b128 v[208:211], v169 offset:17408
	ds_read_b128 v[212:215], v169 offset:18432
	ds_read_b128 v[216:219], v169 offset:19456
	ds_read_b128 v[220:223], v169 offset:20480
	ds_read_b128 v[224:227], v169 offset:21504
	ds_read_b128 v[228:231], v169 offset:22528
	ds_read_b128 v[232:235], v169 offset:23552
	global_load_lds_dwordx4 v132, s[74:75]
	s_add_i32 m0, s88, 0x2000
	s_add_u32 s88, s74, 0x100000
	s_addc_u32 s89, s75, 0
	s_add_i32 s90, s71, s27
	global_load_lds_dwordx4 v136, s[74:75]
	s_mov_b32 m0, s90
	global_load_lds_dwordx4 v132, s[88:89]
	s_add_i32 m0, s90, 0x2000
	s_nop 0
	global_load_lds_dwordx4 v136, s[88:89]
	s_add_u32 s100, s76, 0x80
	s_addc_u32 s101, s77, 0
	s_mov_b32 m0, s59
	s_nop 0
	global_load_lds_dwordx4 v130, s[76:77]
	s_mov_b32 m0, s62
	s_nop 0
	global_load_lds_dwordx4 v134, s[76:77]
	s_waitcnt vmcnt(8)
	s_waitcnt lgkmcnt(0)
	s_barrier
	s_setprio 1
	s_waitcnt lgkmcnt(0)
	v_mfma_f32_16x16x32_bf16 v[62:65], v[150:153], v[204:207], v[62:65]
	v_mfma_f32_16x16x32_bf16 v[62:65], v[172:175], v[208:211], v[62:65]
	v_mfma_f32_16x16x32_bf16 v[58:61], v[176:179], v[204:207], v[58:61]
	v_mfma_f32_16x16x32_bf16 v[58:61], v[184:187], v[208:211], v[58:61]
	v_mfma_f32_16x16x32_bf16 v[50:53], v[150:153], v[212:215], v[50:53]
	v_mfma_f32_16x16x32_bf16 v[50:53], v[172:175], v[216:219], v[50:53]
	v_mfma_f32_16x16x32_bf16 v[42:45], v[176:179], v[212:215], v[42:45]
	v_mfma_f32_16x16x32_bf16 v[42:45], v[184:187], v[216:219], v[42:45]
	v_mfma_f32_16x16x32_bf16 v[34:37], v[150:153], v[220:223], v[34:37]
	v_mfma_f32_16x16x32_bf16 v[34:37], v[172:175], v[224:227], v[34:37]
	v_mfma_f32_16x16x32_bf16 v[26:29], v[176:179], v[220:223], v[26:29]
	v_mfma_f32_16x16x32_bf16 v[26:29], v[184:187], v[224:227], v[26:29]
	v_mfma_f32_16x16x32_bf16 v[18:21], v[150:153], v[228:231], v[18:21]
	v_mfma_f32_16x16x32_bf16 v[18:21], v[172:175], v[232:235], v[18:21]
	v_mfma_f32_16x16x32_bf16 v[10:13], v[176:179], v[228:231], v[10:13]
	v_mfma_f32_16x16x32_bf16 v[10:13], v[184:187], v[232:235], v[10:13]
	s_setprio 0
	s_setprio 1
	v_mfma_f32_16x16x32_bf16 v[54:57], v[188:191], v[204:207], v[54:57]
	v_mfma_f32_16x16x32_bf16 v[54:57], v[192:195], v[208:211], v[54:57]
	v_mfma_f32_16x16x32_bf16 v[46:49], v[196:199], v[204:207], v[46:49]
	v_mfma_f32_16x16x32_bf16 v[46:49], v[200:203], v[208:211], v[46:49]
	v_mfma_f32_16x16x32_bf16 v[38:41], v[188:191], v[212:215], v[38:41]
	v_mfma_f32_16x16x32_bf16 v[38:41], v[192:195], v[216:219], v[38:41]
	v_mfma_f32_16x16x32_bf16 v[30:33], v[196:199], v[212:215], v[30:33]
	v_mfma_f32_16x16x32_bf16 v[30:33], v[200:203], v[216:219], v[30:33]
	v_mfma_f32_16x16x32_bf16 v[22:25], v[188:191], v[220:223], v[22:25]
	v_mfma_f32_16x16x32_bf16 v[22:25], v[192:195], v[224:227], v[22:25]
	v_mfma_f32_16x16x32_bf16 v[14:17], v[196:199], v[220:223], v[14:17]
	v_mfma_f32_16x16x32_bf16 v[14:17], v[200:203], v[224:227], v[14:17]
	v_mfma_f32_16x16x32_bf16 v[6:9], v[188:191], v[228:231], v[6:9]
	v_mfma_f32_16x16x32_bf16 v[6:9], v[192:195], v[232:235], v[6:9]
	v_mfma_f32_16x16x32_bf16 v[2:5], v[196:199], v[228:231], v[2:5]
	v_mfma_f32_16x16x32_bf16 v[2:5], v[200:203], v[232:235], v[2:5]
	s_setprio 0
	s_barrier
	s_add_i32 s88, 0, 0x18000
	v_add_u32_e32 v140, s88, v163
	s_add_i32 s89, 0, 0x1c000
	ds_read_b128 v[150:153], v140
	ds_read_b128 v[172:175], v140 offset:1024
	ds_read_b128 v[176:179], v140 offset:2048
	ds_read_b128 v[184:187], v140 offset:3072
	v_add_u32_e32 v140, s89, v163
	ds_read_b128 v[188:191], v140
	ds_read_b128 v[192:195], v140 offset:1024
	ds_read_b128 v[196:199], v140 offset:2048
	ds_read_b128 v[200:203], v140 offset:3072
	s_add_u32 s76, s76, 0x100000
	s_addc_u32 s77, s77, 0
	s_mov_b32 m0, s63
	ds_read_b128 v[204:207], v169 offset:32768
	ds_read_b128 v[208:211], v169 offset:33792
	ds_read_b128 v[212:215], v169 offset:34816
	ds_read_b128 v[216:219], v169 offset:35840
	ds_read_b128 v[220:223], v169 offset:36864
	ds_read_b128 v[224:227], v169 offset:37888
	ds_read_b128 v[228:231], v169 offset:38912
	ds_read_b128 v[232:235], v169 offset:39936
	global_load_lds_dwordx4 v130, s[76:77]
	s_mov_b32 m0, s65
	s_nop 0
	global_load_lds_dwordx4 v134, s[76:77]
	s_waitcnt vmcnt(8)
	s_waitcnt lgkmcnt(0)
	s_barrier
	s_setprio 1
	s_waitcnt lgkmcnt(0)
	v_mfma_f32_16x16x32_bf16 v[126:129], v[150:153], v[204:207], v[126:129]
	v_mfma_f32_16x16x32_bf16 v[126:129], v[172:175], v[208:211], v[126:129]
	v_mfma_f32_16x16x32_bf16 v[122:125], v[176:179], v[204:207], v[122:125]
	v_mfma_f32_16x16x32_bf16 v[122:125], v[184:187], v[208:211], v[122:125]
	v_mfma_f32_16x16x32_bf16 v[110:113], v[150:153], v[212:215], v[110:113]
	v_mfma_f32_16x16x32_bf16 v[110:113], v[172:175], v[216:219], v[110:113]
	v_mfma_f32_16x16x32_bf16 v[106:109], v[176:179], v[212:215], v[106:109]
	v_mfma_f32_16x16x32_bf16 v[106:109], v[184:187], v[216:219], v[106:109]
	v_mfma_f32_16x16x32_bf16 v[94:97], v[150:153], v[220:223], v[94:97]
	v_mfma_f32_16x16x32_bf16 v[94:97], v[172:175], v[224:227], v[94:97]
	v_mfma_f32_16x16x32_bf16 v[90:93], v[176:179], v[220:223], v[90:93]
	v_mfma_f32_16x16x32_bf16 v[90:93], v[184:187], v[224:227], v[90:93]
	v_mfma_f32_16x16x32_bf16 v[78:81], v[150:153], v[228:231], v[78:81]
	v_mfma_f32_16x16x32_bf16 v[78:81], v[172:175], v[232:235], v[78:81]
	v_mfma_f32_16x16x32_bf16 v[74:77], v[176:179], v[228:231], v[74:77]
	v_mfma_f32_16x16x32_bf16 v[74:77], v[184:187], v[232:235], v[74:77]
	s_setprio 0
	s_setprio 1
	v_mfma_f32_16x16x32_bf16 v[118:121], v[188:191], v[204:207], v[118:121]
	v_mfma_f32_16x16x32_bf16 v[118:121], v[192:195], v[208:211], v[118:121]
	v_mfma_f32_16x16x32_bf16 v[114:117], v[196:199], v[204:207], v[114:117]
	v_mfma_f32_16x16x32_bf16 v[114:117], v[200:203], v[208:211], v[114:117]
	v_mfma_f32_16x16x32_bf16 v[102:105], v[188:191], v[212:215], v[102:105]
	v_mfma_f32_16x16x32_bf16 v[102:105], v[192:195], v[216:219], v[102:105]
	v_mfma_f32_16x16x32_bf16 v[98:101], v[196:199], v[212:215], v[98:101]
	v_mfma_f32_16x16x32_bf16 v[98:101], v[200:203], v[216:219], v[98:101]
	v_mfma_f32_16x16x32_bf16 v[86:89], v[188:191], v[220:223], v[86:89]
	v_mfma_f32_16x16x32_bf16 v[86:89], v[192:195], v[224:227], v[86:89]
	v_mfma_f32_16x16x32_bf16 v[82:85], v[196:199], v[220:223], v[82:85]
	v_mfma_f32_16x16x32_bf16 v[82:85], v[200:203], v[224:227], v[82:85]
	v_mfma_f32_16x16x32_bf16 v[70:73], v[188:191], v[228:231], v[70:73]
	v_mfma_f32_16x16x32_bf16 v[70:73], v[192:195], v[232:235], v[70:73]
	v_mfma_f32_16x16x32_bf16 v[66:69], v[196:199], v[228:231], v[66:69]
	v_mfma_f32_16x16x32_bf16 v[66:69], v[200:203], v[232:235], v[66:69]
	s_setprio 0
	s_barrier
	s_add_i32 s76, s88, s27
	s_mov_b32 m0, s76
	ds_read_b128 v[204:207], v169 offset:49152
	ds_read_b128 v[208:211], v169 offset:50176
	ds_read_b128 v[212:215], v169 offset:51200
	ds_read_b128 v[216:219], v169 offset:52224
	ds_read_b128 v[220:223], v169 offset:53248
	ds_read_b128 v[224:227], v169 offset:54272
	ds_read_b128 v[228:231], v169 offset:55296
	ds_read_b128 v[232:235], v169 offset:56320
	global_load_lds_dwordx4 v132, s[98:99]
	s_add_i32 m0, s76, 0x2000
	s_add_u32 s74, s74, 0x100080
	s_addc_u32 s75, s75, 0
	s_add_i32 s76, s89, s27
	global_load_lds_dwordx4 v136, s[98:99]
	s_mov_b32 m0, s76
	s_nop 0
	global_load_lds_dwordx4 v132, s[74:75]
	s_add_i32 m0, s76, 0x2000
	s_nop 0
	global_load_lds_dwordx4 v136, s[74:75]
	s_mov_b32 m0, s67
	s_nop 0
	global_load_lds_dwordx4 v130, s[100:101]
	s_mov_b32 m0, s68
	s_nop 0
	global_load_lds_dwordx4 v134, s[100:101]
	s_waitcnt vmcnt(8)
	s_waitcnt lgkmcnt(0)
	s_barrier
	s_setprio 1
	s_waitcnt lgkmcnt(0)
	v_mfma_f32_16x16x32_bf16 v[62:65], v[150:153], v[204:207], v[62:65]
	v_mfma_f32_16x16x32_bf16 v[62:65], v[172:175], v[208:211], v[62:65]
	v_mfma_f32_16x16x32_bf16 v[58:61], v[176:179], v[204:207], v[58:61]
	v_mfma_f32_16x16x32_bf16 v[58:61], v[184:187], v[208:211], v[58:61]
	v_mfma_f32_16x16x32_bf16 v[50:53], v[150:153], v[212:215], v[50:53]
	v_mfma_f32_16x16x32_bf16 v[50:53], v[172:175], v[216:219], v[50:53]
	v_mfma_f32_16x16x32_bf16 v[42:45], v[176:179], v[212:215], v[42:45]
	v_mfma_f32_16x16x32_bf16 v[42:45], v[184:187], v[216:219], v[42:45]
	v_mfma_f32_16x16x32_bf16 v[34:37], v[150:153], v[220:223], v[34:37]
	v_mfma_f32_16x16x32_bf16 v[34:37], v[172:175], v[224:227], v[34:37]
	v_mfma_f32_16x16x32_bf16 v[26:29], v[176:179], v[220:223], v[26:29]
	v_mfma_f32_16x16x32_bf16 v[26:29], v[184:187], v[224:227], v[26:29]
	v_mfma_f32_16x16x32_bf16 v[18:21], v[150:153], v[228:231], v[18:21]
	v_mfma_f32_16x16x32_bf16 v[18:21], v[172:175], v[232:235], v[18:21]
	v_mfma_f32_16x16x32_bf16 v[10:13], v[176:179], v[228:231], v[10:13]
	v_mfma_f32_16x16x32_bf16 v[10:13], v[184:187], v[232:235], v[10:13]
	s_setprio 0
	s_setprio 1
	v_mfma_f32_16x16x32_bf16 v[54:57], v[188:191], v[204:207], v[54:57]
	v_mfma_f32_16x16x32_bf16 v[54:57], v[192:195], v[208:211], v[54:57]
	v_mfma_f32_16x16x32_bf16 v[46:49], v[196:199], v[204:207], v[46:49]
	v_mfma_f32_16x16x32_bf16 v[46:49], v[200:203], v[208:211], v[46:49]
	v_mfma_f32_16x16x32_bf16 v[38:41], v[188:191], v[212:215], v[38:41]
	v_mfma_f32_16x16x32_bf16 v[38:41], v[192:195], v[216:219], v[38:41]
	v_mfma_f32_16x16x32_bf16 v[30:33], v[196:199], v[212:215], v[30:33]
	v_mfma_f32_16x16x32_bf16 v[30:33], v[200:203], v[216:219], v[30:33]
	v_mfma_f32_16x16x32_bf16 v[22:25], v[188:191], v[220:223], v[22:25]
	v_mfma_f32_16x16x32_bf16 v[22:25], v[192:195], v[224:227], v[22:25]
	v_mfma_f32_16x16x32_bf16 v[14:17], v[196:199], v[220:223], v[14:17]
	v_mfma_f32_16x16x32_bf16 v[14:17], v[200:203], v[224:227], v[14:17]
	v_mfma_f32_16x16x32_bf16 v[6:9], v[188:191], v[228:231], v[6:9]
	v_mfma_f32_16x16x32_bf16 v[6:9], v[192:195], v[232:235], v[6:9]
	v_mfma_f32_16x16x32_bf16 v[2:5], v[196:199], v[228:231], v[2:5]
	v_mfma_f32_16x16x32_bf16 v[2:5], v[200:203], v[232:235], v[2:5]
	s_setprio 0
	s_barrier
	s_add_i32 s87, s87, 2
	s_add_u32 s6, s6, 0x100
	s_addc_u32 s7, s7, 0
	s_add_u32 s85, s85, 0x100
	s_addc_u32 s86, s86, 0
	s_cmp_gt_u32 s87, 61
	s_cbranch_scc0 .LBB0_2464
	s_and_b64 vcc, exec, s[38:39]
	s_cbranch_vccz .LBB0_2467
	s_barrier

.LBB0_2494:
	ds_read_b128 v[160:163], v155
	ds_read_b128 v[164:167], v155 offset:1024
	ds_read_b128 v[168:171], v155 offset:2048
	ds_read_b128 v[172:175], v155 offset:3072
	ds_read_b128 v[176:179], v156
	ds_read_b128 v[184:187], v156 offset:1024
	ds_read_b128 v[188:191], v156 offset:2048
	ds_read_b128 v[192:195], v156 offset:3072
	s_add_u32 s48, s6, 0xfff00080
	s_addc_u32 s49, s7, -1
	s_cmp_eq_u32 s89, 60
	s_cselect_b32 s51, s43, s49
	s_cselect_b32 s50, s85, s48
	s_cselect_b32 s49, s41, s88
	s_cselect_b32 s48, s86, s87
	s_add_i32 m0, s63, 0xc000
	ds_read_b128 v[196:199], v157
	ds_read_b128 v[200:203], v157 offset:1024
	ds_read_b128 v[204:207], v157 offset:2048
	ds_read_b128 v[208:211], v157 offset:3072
	ds_read_b128 v[212:215], v157 offset:4096
	ds_read_b128 v[216:219], v157 offset:5120
	ds_read_b128 v[220:223], v157 offset:6144
	ds_read_b128 v[224:227], v157 offset:7168
	global_load_lds_dwordx4 v140, s[6:7]
	s_add_i32 m0, s63, 0xe000
	s_nop 0
	global_load_lds_dwordx4 v142, s[6:7]
	s_waitcnt vmcnt(8)
	s_waitcnt lgkmcnt(0)
	s_barrier
	s_setprio 1
	s_waitcnt lgkmcnt(0)
	v_mfma_f32_16x16x32_bf16 v[126:129], v[160:163], v[196:199], v[126:129]
	v_mfma_f32_16x16x32_bf16 v[126:129], v[164:167], v[200:203], v[126:129]
	v_mfma_f32_16x16x32_bf16 v[122:125], v[168:171], v[196:199], v[122:125]
	v_mfma_f32_16x16x32_bf16 v[122:125], v[172:175], v[200:203], v[122:125]
	v_mfma_f32_16x16x32_bf16 v[110:113], v[160:163], v[204:207], v[110:113]
	v_mfma_f32_16x16x32_bf16 v[110:113], v[164:167], v[208:211], v[110:113]
	v_mfma_f32_16x16x32_bf16 v[106:109], v[168:171], v[204:207], v[106:109]
	v_mfma_f32_16x16x32_bf16 v[106:109], v[172:175], v[208:211], v[106:109]
	v_mfma_f32_16x16x32_bf16 v[94:97], v[160:163], v[212:215], v[94:97]
	v_mfma_f32_16x16x32_bf16 v[94:97], v[164:167], v[216:219], v[94:97]
	v_mfma_f32_16x16x32_bf16 v[90:93], v[168:171], v[212:215], v[90:93]
	v_mfma_f32_16x16x32_bf16 v[90:93], v[172:175], v[216:219], v[90:93]
	v_mfma_f32_16x16x32_bf16 v[78:81], v[160:163], v[220:223], v[78:81]
	v_mfma_f32_16x16x32_bf16 v[78:81], v[164:167], v[224:227], v[78:81]
	v_mfma_f32_16x16x32_bf16 v[74:77], v[168:171], v[220:223], v[74:77]
	v_mfma_f32_16x16x32_bf16 v[74:77], v[172:175], v[224:227], v[74:77]
	s_setprio 0
	s_setprio 1
	v_mfma_f32_16x16x32_bf16 v[118:121], v[176:179], v[196:199], v[118:121]
	v_mfma_f32_16x16x32_bf16 v[118:121], v[184:187], v[200:203], v[118:121]
	v_mfma_f32_16x16x32_bf16 v[114:117], v[188:191], v[196:199], v[114:117]
	v_mfma_f32_16x16x32_bf16 v[114:117], v[192:195], v[200:203], v[114:117]
	v_mfma_f32_16x16x32_bf16 v[102:105], v[176:179], v[204:207], v[102:105]
	v_mfma_f32_16x16x32_bf16 v[102:105], v[184:187], v[208:211], v[102:105]
	v_mfma_f32_16x16x32_bf16 v[98:101], v[188:191], v[204:207], v[98:101]
	v_mfma_f32_16x16x32_bf16 v[98:101], v[192:195], v[208:211], v[98:101]
	v_mfma_f32_16x16x32_bf16 v[86:89], v[176:179], v[212:215], v[86:89]
	v_mfma_f32_16x16x32_bf16 v[86:89], v[184:187], v[216:219], v[86:89]
	v_mfma_f32_16x16x32_bf16 v[82:85], v[188:191], v[212:215], v[82:85]
	v_mfma_f32_16x16x32_bf16 v[82:85], v[192:195], v[216:219], v[82:85]
	v_mfma_f32_16x16x32_bf16 v[70:73], v[176:179], v[220:223], v[70:73]
	v_mfma_f32_16x16x32_bf16 v[70:73], v[184:187], v[224:227], v[70:73]
	v_mfma_f32_16x16x32_bf16 v[66:69], v[188:191], v[220:223], v[66:69]
	v_mfma_f32_16x16x32_bf16 v[66:69], v[192:195], v[224:227], v[66:69]
	s_setprio 0
	s_barrier
	s_add_i32 s90, s73, s27
	s_add_u32 s98, s48, 0x80
	s_addc_u32 s99, s49, 0
	s_mov_b32 m0, s90
	ds_read_b128 v[196:199], v157 offset:16384
	ds_read_b128 v[200:203], v157 offset:17408
	ds_read_b128 v[204:207], v157 offset:18432
	ds_read_b128 v[208:211], v157 offset:19456
	ds_read_b128 v[212:215], v157 offset:20480
	ds_read_b128 v[216:219], v157 offset:21504
	ds_read_b128 v[220:223], v157 offset:22528
	ds_read_b128 v[224:227], v157 offset:23552
	global_load_lds_dwordx4 v132, s[48:49]
	s_add_i32 m0, s90, 0x2000
	s_add_u32 s90, s48, 0x100000
	s_addc_u32 s91, s49, 0
	s_add_i32 s92, s74, s27
	global_load_lds_dwordx4 v136, s[48:49]
	s_mov_b32 m0, s92
	global_load_lds_dwordx4 v132, s[90:91]
	s_add_i32 m0, s92, 0x2000
	s_nop 0
	global_load_lds_dwordx4 v136, s[90:91]
	s_add_u32 s100, s50, 0x80
	s_addc_u32 s101, s51, 0
	s_mov_b32 m0, s63
	s_nop 0
	global_load_lds_dwordx4 v130, s[50:51]
	s_mov_b32 m0, s65
	s_nop 0
	global_load_lds_dwordx4 v134, s[50:51]
	s_waitcnt vmcnt(8)
	s_waitcnt lgkmcnt(0)
	s_barrier
	s_setprio 1
	s_waitcnt lgkmcnt(0)
	v_mfma_f32_16x16x32_bf16 v[62:65], v[160:163], v[196:199], v[62:65]
	v_mfma_f32_16x16x32_bf16 v[62:65], v[164:167], v[200:203], v[62:65]
	v_mfma_f32_16x16x32_bf16 v[58:61], v[168:171], v[196:199], v[58:61]
	v_mfma_f32_16x16x32_bf16 v[58:61], v[172:175], v[200:203], v[58:61]
	v_mfma_f32_16x16x32_bf16 v[50:53], v[160:163], v[204:207], v[50:53]
	v_mfma_f32_16x16x32_bf16 v[50:53], v[164:167], v[208:211], v[50:53]
	v_mfma_f32_16x16x32_bf16 v[42:45], v[168:171], v[204:207], v[42:45]
	v_mfma_f32_16x16x32_bf16 v[42:45], v[172:175], v[208:211], v[42:45]
	v_mfma_f32_16x16x32_bf16 v[34:37], v[160:163], v[212:215], v[34:37]
	v_mfma_f32_16x16x32_bf16 v[34:37], v[164:167], v[216:219], v[34:37]
	v_mfma_f32_16x16x32_bf16 v[26:29], v[168:171], v[212:215], v[26:29]
	v_mfma_f32_16x16x32_bf16 v[26:29], v[172:175], v[216:219], v[26:29]
	v_mfma_f32_16x16x32_bf16 v[18:21], v[160:163], v[220:223], v[18:21]
	v_mfma_f32_16x16x32_bf16 v[18:21], v[164:167], v[224:227], v[18:21]
	v_mfma_f32_16x16x32_bf16 v[10:13], v[168:171], v[220:223], v[10:13]
	v_mfma_f32_16x16x32_bf16 v[10:13], v[172:175], v[224:227], v[10:13]
	s_setprio 0
	s_setprio 1
	v_mfma_f32_16x16x32_bf16 v[54:57], v[176:179], v[196:199], v[54:57]
	v_mfma_f32_16x16x32_bf16 v[54:57], v[184:187], v[200:203], v[54:57]
	v_mfma_f32_16x16x32_bf16 v[46:49], v[188:191], v[196:199], v[46:49]
	v_mfma_f32_16x16x32_bf16 v[46:49], v[192:195], v[200:203], v[46:49]
	v_mfma_f32_16x16x32_bf16 v[38:41], v[176:179], v[204:207], v[38:41]
	v_mfma_f32_16x16x32_bf16 v[38:41], v[184:187], v[208:211], v[38:41]
	v_mfma_f32_16x16x32_bf16 v[30:33], v[188:191], v[204:207], v[30:33]
	v_mfma_f32_16x16x32_bf16 v[30:33], v[192:195], v[208:211], v[30:33]
	v_mfma_f32_16x16x32_bf16 v[22:25], v[176:179], v[212:215], v[22:25]
	v_mfma_f32_16x16x32_bf16 v[22:25], v[184:187], v[216:219], v[22:25]
	v_mfma_f32_16x16x32_bf16 v[14:17], v[188:191], v[212:215], v[14:17]
	v_mfma_f32_16x16x32_bf16 v[14:17], v[192:195], v[216:219], v[14:17]
	v_mfma_f32_16x16x32_bf16 v[6:9], v[176:179], v[220:223], v[6:9]
	v_mfma_f32_16x16x32_bf16 v[6:9], v[184:187], v[224:227], v[6:9]
	v_mfma_f32_16x16x32_bf16 v[2:5], v[188:191], v[220:223], v[2:5]
	v_mfma_f32_16x16x32_bf16 v[2:5], v[192:195], v[224:227], v[2:5]
	s_setprio 0
	s_barrier
	s_add_i32 s90, 0, 0x18000
	v_add_u32_e32 v138, s90, v151
	s_add_i32 s91, 0, 0x1c000
	ds_read_b128 v[160:163], v138
	ds_read_b128 v[164:167], v138 offset:1024
	ds_read_b128 v[168:171], v138 offset:2048
	ds_read_b128 v[172:175], v138 offset:3072
	v_add_u32_e32 v138, s91, v151
	ds_read_b128 v[176:179], v138
	ds_read_b128 v[184:187], v138 offset:1024
	ds_read_b128 v[188:191], v138 offset:2048
	ds_read_b128 v[192:195], v138 offset:3072
	s_add_u32 s50, s50, 0x100000
	s_addc_u32 s51, s51, 0
	s_mov_b32 m0, s66
	ds_read_b128 v[196:199], v157 offset:32768
	ds_read_b128 v[200:203], v157 offset:33792
	ds_read_b128 v[204:207], v157 offset:34816
	ds_read_b128 v[208:211], v157 offset:35840
	ds_read_b128 v[212:215], v157 offset:36864
	ds_read_b128 v[216:219], v157 offset:37888
	ds_read_b128 v[220:223], v157 offset:38912
	ds_read_b128 v[224:227], v157 offset:39936
	global_load_lds_dwordx4 v130, s[50:51]
	s_mov_b32 m0, s67
	s_nop 0
	global_load_lds_dwordx4 v134, s[50:51]
	s_waitcnt vmcnt(8)
	s_waitcnt lgkmcnt(0)
	s_barrier
	s_setprio 1
	s_waitcnt lgkmcnt(0)
	v_mfma_f32_16x16x32_bf16 v[126:129], v[160:163], v[196:199], v[126:129]
	v_mfma_f32_16x16x32_bf16 v[126:129], v[164:167], v[200:203], v[126:129]
	v_mfma_f32_16x16x32_bf16 v[122:125], v[168:171], v[196:199], v[122:125]
	v_mfma_f32_16x16x32_bf16 v[122:125], v[172:175], v[200:203], v[122:125]
	v_mfma_f32_16x16x32_bf16 v[110:113], v[160:163], v[204:207], v[110:113]
	v_mfma_f32_16x16x32_bf16 v[110:113], v[164:167], v[208:211], v[110:113]
	v_mfma_f32_16x16x32_bf16 v[106:109], v[168:171], v[204:207], v[106:109]
	v_mfma_f32_16x16x32_bf16 v[106:109], v[172:175], v[208:211], v[106:109]
	v_mfma_f32_16x16x32_bf16 v[94:97], v[160:163], v[212:215], v[94:97]
	v_mfma_f32_16x16x32_bf16 v[94:97], v[164:167], v[216:219], v[94:97]
	v_mfma_f32_16x16x32_bf16 v[90:93], v[168:171], v[212:215], v[90:93]
	v_mfma_f32_16x16x32_bf16 v[90:93], v[172:175], v[216:219], v[90:93]
	v_mfma_f32_16x16x32_bf16 v[78:81], v[160:163], v[220:223], v[78:81]
	v_mfma_f32_16x16x32_bf16 v[78:81], v[164:167], v[224:227], v[78:81]
	v_mfma_f32_16x16x32_bf16 v[74:77], v[168:171], v[220:223], v[74:77]
	v_mfma_f32_16x16x32_bf16 v[74:77], v[172:175], v[224:227], v[74:77]
	s_setprio 0
	s_setprio 1
	v_mfma_f32_16x16x32_bf16 v[118:121], v[176:179], v[196:199], v[118:121]
	v_mfma_f32_16x16x32_bf16 v[118:121], v[184:187], v[200:203], v[118:121]
	v_mfma_f32_16x16x32_bf16 v[114:117], v[188:191], v[196:199], v[114:117]
	v_mfma_f32_16x16x32_bf16 v[114:117], v[192:195], v[200:203], v[114:117]
	v_mfma_f32_16x16x32_bf16 v[102:105], v[176:179], v[204:207], v[102:105]
	v_mfma_f32_16x16x32_bf16 v[102:105], v[184:187], v[208:211], v[102:105]
	v_mfma_f32_16x16x32_bf16 v[98:101], v[188:191], v[204:207], v[98:101]
	v_mfma_f32_16x16x32_bf16 v[98:101], v[192:195], v[208:211], v[98:101]
	v_mfma_f32_16x16x32_bf16 v[86:89], v[176:179], v[212:215], v[86:89]
	v_mfma_f32_16x16x32_bf16 v[86:89], v[184:187], v[216:219], v[86:89]
	v_mfma_f32_16x16x32_bf16 v[82:85], v[188:191], v[212:215], v[82:85]
	v_mfma_f32_16x16x32_bf16 v[82:85], v[192:195], v[216:219], v[82:85]
	v_mfma_f32_16x16x32_bf16 v[70:73], v[176:179], v[220:223], v[70:73]
	v_mfma_f32_16x16x32_bf16 v[70:73], v[184:187], v[224:227], v[70:73]
	v_mfma_f32_16x16x32_bf16 v[66:69], v[188:191], v[220:223], v[66:69]
	v_mfma_f32_16x16x32_bf16 v[66:69], v[192:195], v[224:227], v[66:69]
	s_setprio 0
	s_barrier
	s_add_i32 s50, s90, s27
	s_mov_b32 m0, s50
	ds_read_b128 v[196:199], v157 offset:49152
	ds_read_b128 v[200:203], v157 offset:50176
	ds_read_b128 v[204:207], v157 offset:51200
	ds_read_b128 v[208:211], v157 offset:52224
	ds_read_b128 v[212:215], v157 offset:53248
	ds_read_b128 v[216:219], v157 offset:54272
	ds_read_b128 v[220:223], v157 offset:55296
	ds_read_b128 v[224:227], v157 offset:56320
	global_load_lds_dwordx4 v132, s[98:99]
	s_add_i32 m0, s50, 0x2000
	s_add_u32 s48, s48, 0x100080
	s_addc_u32 s49, s49, 0
	s_add_i32 s50, s91, s27
	global_load_lds_dwordx4 v136, s[98:99]
	s_mov_b32 m0, s50
	s_nop 0
	global_load_lds_dwordx4 v132, s[48:49]
	s_add_i32 m0, s50, 0x2000
	s_nop 0
	global_load_lds_dwordx4 v136, s[48:49]
	s_mov_b32 m0, s69
	s_nop 0
	global_load_lds_dwordx4 v130, s[100:101]
	s_mov_b32 m0, s70
	s_nop 0
	global_load_lds_dwordx4 v134, s[100:101]
	s_waitcnt vmcnt(8)
	s_waitcnt lgkmcnt(0)
	s_barrier
	s_setprio 1
	s_waitcnt lgkmcnt(0)
	v_mfma_f32_16x16x32_bf16 v[62:65], v[160:163], v[196:199], v[62:65]
	v_mfma_f32_16x16x32_bf16 v[62:65], v[164:167], v[200:203], v[62:65]
	v_mfma_f32_16x16x32_bf16 v[58:61], v[168:171], v[196:199], v[58:61]
	v_mfma_f32_16x16x32_bf16 v[58:61], v[172:175], v[200:203], v[58:61]
	v_mfma_f32_16x16x32_bf16 v[50:53], v[160:163], v[204:207], v[50:53]
	v_mfma_f32_16x16x32_bf16 v[50:53], v[164:167], v[208:211], v[50:53]
	v_mfma_f32_16x16x32_bf16 v[42:45], v[168:171], v[204:207], v[42:45]
	v_mfma_f32_16x16x32_bf16 v[42:45], v[172:175], v[208:211], v[42:45]
	v_mfma_f32_16x16x32_bf16 v[34:37], v[160:163], v[212:215], v[34:37]
	v_mfma_f32_16x16x32_bf16 v[34:37], v[164:167], v[216:219], v[34:37]
	v_mfma_f32_16x16x32_bf16 v[26:29], v[168:171], v[212:215], v[26:29]
	v_mfma_f32_16x16x32_bf16 v[26:29], v[172:175], v[216:219], v[26:29]
	v_mfma_f32_16x16x32_bf16 v[18:21], v[160:163], v[220:223], v[18:21]
	v_mfma_f32_16x16x32_bf16 v[18:21], v[164:167], v[224:227], v[18:21]
	v_mfma_f32_16x16x32_bf16 v[10:13], v[168:171], v[220:223], v[10:13]
	v_mfma_f32_16x16x32_bf16 v[10:13], v[172:175], v[224:227], v[10:13]
	s_setprio 0
	s_setprio 1
	v_mfma_f32_16x16x32_bf16 v[54:57], v[176:179], v[196:199], v[54:57]
	v_mfma_f32_16x16x32_bf16 v[54:57], v[184:187], v[200:203], v[54:57]
	v_mfma_f32_16x16x32_bf16 v[46:49], v[188:191], v[196:199], v[46:49]
	v_mfma_f32_16x16x32_bf16 v[46:49], v[192:195], v[200:203], v[46:49]
	v_mfma_f32_16x16x32_bf16 v[38:41], v[176:179], v[204:207], v[38:41]
	v_mfma_f32_16x16x32_bf16 v[38:41], v[184:187], v[208:211], v[38:41]
	v_mfma_f32_16x16x32_bf16 v[30:33], v[188:191], v[204:207], v[30:33]
	v_mfma_f32_16x16x32_bf16 v[30:33], v[192:195], v[208:211], v[30:33]
	v_mfma_f32_16x16x32_bf16 v[22:25], v[176:179], v[212:215], v[22:25]
	v_mfma_f32_16x16x32_bf16 v[22:25], v[184:187], v[216:219], v[22:25]
	v_mfma_f32_16x16x32_bf16 v[14:17], v[188:191], v[212:215], v[14:17]
	v_mfma_f32_16x16x32_bf16 v[14:17], v[192:195], v[216:219], v[14:17]
	v_mfma_f32_16x16x32_bf16 v[6:9], v[176:179], v[220:223], v[6:9]
	v_mfma_f32_16x16x32_bf16 v[6:9], v[184:187], v[224:227], v[6:9]
	v_mfma_f32_16x16x32_bf16 v[2:5], v[188:191], v[220:223], v[2:5]
	v_mfma_f32_16x16x32_bf16 v[2:5], v[192:195], v[224:227], v[2:5]
	s_setprio 0
	s_barrier
	s_add_i32 s89, s89, 2
	s_add_u32 s6, s6, 0x100
	s_addc_u32 s7, s7, 0
	s_add_u32 s87, s87, 0x100
	s_addc_u32 s88, s88, 0
	s_cmp_gt_u32 s89, 61
	s_cbranch_scc0 .LBB0_2494
	s_and_b64 vcc, exec, s[38:39]
	s_cbranch_vccz .LBB0_2497
	s_barrier

.LBB0_2635:
	ds_read_b128 v[130:133], v163
	ds_read_b128 v[134:137], v163 offset:1024
	ds_read_b128 v[138:141], v163 offset:2048
	ds_read_b128 v[142:145], v163 offset:3072
	ds_read_b128 v[146:149], v188
	ds_read_b128 v[150:153], v188 offset:1024
	ds_read_b128 v[174:177], v188 offset:2048
	ds_read_b128 v[178:181], v188 offset:3072
	s_add_u32 s48, s46, 0xfff00080
	s_addc_u32 s49, s47, -1
	s_cmp_eq_u32 s73, 60
	s_cselect_b32 s51, s22, s49
	s_cselect_b32 s50, s41, s48
	s_cselect_b32 s49, s39, s72
	s_cselect_b32 s48, s70, s71
	s_add_i32 m0, s13, 0xc000
	ds_read_b128 v[184:187], v189
	ds_read_b128 v[192:195], v189 offset:1024
	ds_read_b128 v[196:199], v189 offset:2048
	ds_read_b128 v[200:203], v189 offset:3072
	ds_read_b128 v[204:207], v189 offset:4096
	ds_read_b128 v[208:211], v189 offset:5120
	ds_read_b128 v[212:215], v189 offset:6144
	ds_read_b128 v[216:219], v189 offset:7168
	global_load_lds_dwordx4 v166, s[46:47]
	s_add_i32 m0, s13, 0xe000
	s_nop 0
	global_load_lds_dwordx4 v168, s[46:47]
	s_waitcnt vmcnt(8)
	s_waitcnt lgkmcnt(0)
	s_barrier
	s_setprio 1
	s_waitcnt lgkmcnt(0)
	v_mfma_f32_16x16x32_bf16 v[126:129], v[130:133], v[184:187], v[126:129]
	v_mfma_f32_16x16x32_bf16 v[126:129], v[134:137], v[192:195], v[126:129]
	v_mfma_f32_16x16x32_bf16 v[122:125], v[138:141], v[184:187], v[122:125]
	v_mfma_f32_16x16x32_bf16 v[122:125], v[142:145], v[192:195], v[122:125]
	v_mfma_f32_16x16x32_bf16 v[110:113], v[130:133], v[196:199], v[110:113]
	v_mfma_f32_16x16x32_bf16 v[110:113], v[134:137], v[200:203], v[110:113]
	v_mfma_f32_16x16x32_bf16 v[106:109], v[138:141], v[196:199], v[106:109]
	v_mfma_f32_16x16x32_bf16 v[106:109], v[142:145], v[200:203], v[106:109]
	v_mfma_f32_16x16x32_bf16 v[94:97], v[130:133], v[204:207], v[94:97]
	v_mfma_f32_16x16x32_bf16 v[94:97], v[134:137], v[208:211], v[94:97]
	v_mfma_f32_16x16x32_bf16 v[90:93], v[138:141], v[204:207], v[90:93]
	v_mfma_f32_16x16x32_bf16 v[90:93], v[142:145], v[208:211], v[90:93]
	v_mfma_f32_16x16x32_bf16 v[78:81], v[130:133], v[212:215], v[78:81]
	v_mfma_f32_16x16x32_bf16 v[78:81], v[134:137], v[216:219], v[78:81]
	v_mfma_f32_16x16x32_bf16 v[74:77], v[138:141], v[212:215], v[74:77]
	v_mfma_f32_16x16x32_bf16 v[74:77], v[142:145], v[216:219], v[74:77]
	s_setprio 0
	s_setprio 1
	v_mfma_f32_16x16x32_bf16 v[118:121], v[146:149], v[184:187], v[118:121]
	v_mfma_f32_16x16x32_bf16 v[118:121], v[150:153], v[192:195], v[118:121]
	v_mfma_f32_16x16x32_bf16 v[114:117], v[174:177], v[184:187], v[114:117]
	v_mfma_f32_16x16x32_bf16 v[114:117], v[178:181], v[192:195], v[114:117]
	v_mfma_f32_16x16x32_bf16 v[102:105], v[146:149], v[196:199], v[102:105]
	v_mfma_f32_16x16x32_bf16 v[102:105], v[150:153], v[200:203], v[102:105]
	v_mfma_f32_16x16x32_bf16 v[98:101], v[174:177], v[196:199], v[98:101]
	v_mfma_f32_16x16x32_bf16 v[98:101], v[178:181], v[200:203], v[98:101]
	v_mfma_f32_16x16x32_bf16 v[86:89], v[146:149], v[204:207], v[86:89]
	v_mfma_f32_16x16x32_bf16 v[86:89], v[150:153], v[208:211], v[86:89]
	v_mfma_f32_16x16x32_bf16 v[82:85], v[174:177], v[204:207], v[82:85]
	v_mfma_f32_16x16x32_bf16 v[82:85], v[178:181], v[208:211], v[82:85]
	v_mfma_f32_16x16x32_bf16 v[70:73], v[146:149], v[212:215], v[70:73]
	v_mfma_f32_16x16x32_bf16 v[70:73], v[150:153], v[216:219], v[70:73]
	v_mfma_f32_16x16x32_bf16 v[66:69], v[174:177], v[212:215], v[66:69]
	v_mfma_f32_16x16x32_bf16 v[66:69], v[178:181], v[216:219], v[66:69]
	s_setprio 0
	s_barrier
	s_add_i32 s74, s67, s3
	s_add_u32 s98, s48, 0x80
	s_addc_u32 s99, s49, 0
	s_mov_b32 m0, s74
	ds_read_b128 v[184:187], v189 offset:16384
	ds_read_b128 v[192:195], v189 offset:17408
	ds_read_b128 v[196:199], v189 offset:18432
	ds_read_b128 v[200:203], v189 offset:19456
	ds_read_b128 v[204:207], v189 offset:20480
	ds_read_b128 v[208:211], v189 offset:21504
	ds_read_b128 v[212:215], v189 offset:22528
	ds_read_b128 v[216:219], v189 offset:23552
	global_load_lds_dwordx4 v156, s[48:49]
	s_add_i32 m0, s74, 0x2000
	s_add_u32 s74, s48, 0x100000
	s_addc_u32 s75, s49, 0
	s_add_i32 s76, s68, s3
	global_load_lds_dwordx4 v160, s[48:49]
	s_mov_b32 m0, s76
	global_load_lds_dwordx4 v156, s[74:75]
	s_add_i32 m0, s76, 0x2000
	s_nop 0
	global_load_lds_dwordx4 v160, s[74:75]
	s_add_u32 s100, s50, 0x80
	s_addc_u32 s101, s51, 0
	s_mov_b32 m0, s13
	s_nop 0
	global_load_lds_dwordx4 v154, s[50:51]
	s_mov_b32 m0, s21
	s_nop 0
	global_load_lds_dwordx4 v158, s[50:51]
	s_waitcnt vmcnt(8)
	s_waitcnt lgkmcnt(0)
	s_barrier
	s_setprio 1
	s_waitcnt lgkmcnt(0)
	v_mfma_f32_16x16x32_bf16 v[62:65], v[130:133], v[184:187], v[62:65]
	v_mfma_f32_16x16x32_bf16 v[62:65], v[134:137], v[192:195], v[62:65]
	v_mfma_f32_16x16x32_bf16 v[58:61], v[138:141], v[184:187], v[58:61]
	v_mfma_f32_16x16x32_bf16 v[58:61], v[142:145], v[192:195], v[58:61]
	v_mfma_f32_16x16x32_bf16 v[46:49], v[130:133], v[196:199], v[46:49]
	v_mfma_f32_16x16x32_bf16 v[46:49], v[134:137], v[200:203], v[46:49]
	v_mfma_f32_16x16x32_bf16 v[42:45], v[138:141], v[196:199], v[42:45]
	v_mfma_f32_16x16x32_bf16 v[42:45], v[142:145], v[200:203], v[42:45]
	v_mfma_f32_16x16x32_bf16 v[30:33], v[130:133], v[204:207], v[30:33]
	v_mfma_f32_16x16x32_bf16 v[30:33], v[134:137], v[208:211], v[30:33]
	v_mfma_f32_16x16x32_bf16 v[26:29], v[138:141], v[204:207], v[26:29]
	v_mfma_f32_16x16x32_bf16 v[26:29], v[142:145], v[208:211], v[26:29]
	v_mfma_f32_16x16x32_bf16 v[14:17], v[130:133], v[212:215], v[14:17]
	v_mfma_f32_16x16x32_bf16 v[14:17], v[134:137], v[216:219], v[14:17]
	v_mfma_f32_16x16x32_bf16 v[10:13], v[138:141], v[212:215], v[10:13]
	v_mfma_f32_16x16x32_bf16 v[10:13], v[142:145], v[216:219], v[10:13]
	s_setprio 0
	s_setprio 1
	v_mfma_f32_16x16x32_bf16 v[54:57], v[146:149], v[184:187], v[54:57]
	v_mfma_f32_16x16x32_bf16 v[54:57], v[150:153], v[192:195], v[54:57]
	v_mfma_f32_16x16x32_bf16 v[50:53], v[174:177], v[184:187], v[50:53]
	v_mfma_f32_16x16x32_bf16 v[50:53], v[178:181], v[192:195], v[50:53]
	v_mfma_f32_16x16x32_bf16 v[38:41], v[146:149], v[196:199], v[38:41]
	v_mfma_f32_16x16x32_bf16 v[38:41], v[150:153], v[200:203], v[38:41]
	v_mfma_f32_16x16x32_bf16 v[34:37], v[174:177], v[196:199], v[34:37]
	v_mfma_f32_16x16x32_bf16 v[34:37], v[178:181], v[200:203], v[34:37]
	v_mfma_f32_16x16x32_bf16 v[22:25], v[146:149], v[204:207], v[22:25]
	v_mfma_f32_16x16x32_bf16 v[22:25], v[150:153], v[208:211], v[22:25]
	v_mfma_f32_16x16x32_bf16 v[18:21], v[174:177], v[204:207], v[18:21]
	v_mfma_f32_16x16x32_bf16 v[18:21], v[178:181], v[208:211], v[18:21]
	v_mfma_f32_16x16x32_bf16 v[6:9], v[146:149], v[212:215], v[6:9]
	v_mfma_f32_16x16x32_bf16 v[6:9], v[150:153], v[216:219], v[6:9]
	v_mfma_f32_16x16x32_bf16 v[2:5], v[174:177], v[212:215], v[2:5]
	v_mfma_f32_16x16x32_bf16 v[2:5], v[178:181], v[216:219], v[2:5]
	s_setprio 0
	s_barrier
	s_add_i32 s74, 0, 0x18000
	s_add_i32 s75, 0, 0x1c000
	v_add_u32_e32 v142, s74, v1
	v_add_u32_e32 v178, s75, v1
	ds_read_b128 v[130:133], v142
	ds_read_b128 v[134:137], v142 offset:1024
	ds_read_b128 v[138:141], v142 offset:2048
	ds_read_b128 v[142:145], v142 offset:3072
	ds_read_b128 v[146:149], v178
	ds_read_b128 v[150:153], v178 offset:1024
	ds_read_b128 v[174:177], v178 offset:2048
	ds_read_b128 v[178:181], v178 offset:3072
	s_add_u32 s50, s50, 0x100000
	s_addc_u32 s51, s51, 0
	s_mov_b32 m0, s33
	ds_read_b128 v[184:187], v189 offset:32768
	ds_read_b128 v[192:195], v189 offset:33792
	ds_read_b128 v[196:199], v189 offset:34816
	ds_read_b128 v[200:203], v189 offset:35840
	ds_read_b128 v[204:207], v189 offset:36864
	ds_read_b128 v[208:211], v189 offset:37888
	ds_read_b128 v[212:215], v189 offset:38912
	ds_read_b128 v[216:219], v189 offset:39936
	global_load_lds_dwordx4 v154, s[50:51]
	s_mov_b32 m0, s35
	s_nop 0
	global_load_lds_dwordx4 v158, s[50:51]
	s_waitcnt vmcnt(8)
	s_waitcnt lgkmcnt(0)
	s_barrier
	s_setprio 1
	s_waitcnt lgkmcnt(0)
	v_mfma_f32_16x16x32_bf16 v[126:129], v[130:133], v[184:187], v[126:129]
	v_mfma_f32_16x16x32_bf16 v[126:129], v[134:137], v[192:195], v[126:129]
	v_mfma_f32_16x16x32_bf16 v[122:125], v[138:141], v[184:187], v[122:125]
	v_mfma_f32_16x16x32_bf16 v[122:125], v[142:145], v[192:195], v[122:125]
	v_mfma_f32_16x16x32_bf16 v[110:113], v[130:133], v[196:199], v[110:113]
	v_mfma_f32_16x16x32_bf16 v[110:113], v[134:137], v[200:203], v[110:113]
	v_mfma_f32_16x16x32_bf16 v[106:109], v[138:141], v[196:199], v[106:109]
	v_mfma_f32_16x16x32_bf16 v[106:109], v[142:145], v[200:203], v[106:109]
	v_mfma_f32_16x16x32_bf16 v[94:97], v[130:133], v[204:207], v[94:97]
	v_mfma_f32_16x16x32_bf16 v[94:97], v[134:137], v[208:211], v[94:97]
	v_mfma_f32_16x16x32_bf16 v[90:93], v[138:141], v[204:207], v[90:93]
	v_mfma_f32_16x16x32_bf16 v[90:93], v[142:145], v[208:211], v[90:93]
	v_mfma_f32_16x16x32_bf16 v[78:81], v[130:133], v[212:215], v[78:81]
	v_mfma_f32_16x16x32_bf16 v[78:81], v[134:137], v[216:219], v[78:81]
	v_mfma_f32_16x16x32_bf16 v[74:77], v[138:141], v[212:215], v[74:77]
	v_mfma_f32_16x16x32_bf16 v[74:77], v[142:145], v[216:219], v[74:77]
	s_setprio 0
	s_setprio 1
	v_mfma_f32_16x16x32_bf16 v[118:121], v[146:149], v[184:187], v[118:121]
	v_mfma_f32_16x16x32_bf16 v[118:121], v[150:153], v[192:195], v[118:121]
	v_mfma_f32_16x16x32_bf16 v[114:117], v[174:177], v[184:187], v[114:117]
	v_mfma_f32_16x16x32_bf16 v[114:117], v[178:181], v[192:195], v[114:117]
	v_mfma_f32_16x16x32_bf16 v[102:105], v[146:149], v[196:199], v[102:105]
	v_mfma_f32_16x16x32_bf16 v[102:105], v[150:153], v[200:203], v[102:105]
	v_mfma_f32_16x16x32_bf16 v[98:101], v[174:177], v[196:199], v[98:101]
	v_mfma_f32_16x16x32_bf16 v[98:101], v[178:181], v[200:203], v[98:101]
	v_mfma_f32_16x16x32_bf16 v[86:89], v[146:149], v[204:207], v[86:89]
	v_mfma_f32_16x16x32_bf16 v[86:89], v[150:153], v[208:211], v[86:89]
	v_mfma_f32_16x16x32_bf16 v[82:85], v[174:177], v[204:207], v[82:85]
	v_mfma_f32_16x16x32_bf16 v[82:85], v[178:181], v[208:211], v[82:85]
	v_mfma_f32_16x16x32_bf16 v[70:73], v[146:149], v[212:215], v[70:73]
	v_mfma_f32_16x16x32_bf16 v[70:73], v[150:153], v[216:219], v[70:73]
	v_mfma_f32_16x16x32_bf16 v[66:69], v[174:177], v[212:215], v[66:69]
	v_mfma_f32_16x16x32_bf16 v[66:69], v[178:181], v[216:219], v[66:69]
	s_setprio 0
	s_barrier
	s_add_i32 s50, s74, s3
	s_mov_b32 m0, s50
	ds_read_b128 v[184:187], v189 offset:49152
	ds_read_b128 v[192:195], v189 offset:50176
	ds_read_b128 v[196:199], v189 offset:51200
	ds_read_b128 v[200:203], v189 offset:52224
	ds_read_b128 v[204:207], v189 offset:53248
	ds_read_b128 v[208:211], v189 offset:54272
	ds_read_b128 v[212:215], v189 offset:55296
	ds_read_b128 v[216:219], v189 offset:56320
	global_load_lds_dwordx4 v156, s[98:99]
	s_add_i32 m0, s50, 0x2000
	s_add_u32 s48, s48, 0x100080
	s_addc_u32 s49, s49, 0
	s_add_i32 s50, s75, s3
	global_load_lds_dwordx4 v160, s[98:99]
	s_mov_b32 m0, s50
	s_nop 0
	global_load_lds_dwordx4 v156, s[48:49]
	s_add_i32 m0, s50, 0x2000
	s_nop 0
	global_load_lds_dwordx4 v160, s[48:49]
	s_mov_b32 m0, s62
	s_nop 0
	global_load_lds_dwordx4 v154, s[100:101]
	s_mov_b32 m0, s63
	s_nop 0
	global_load_lds_dwordx4 v158, s[100:101]
	s_waitcnt vmcnt(8)
	s_waitcnt lgkmcnt(0)
	s_barrier
	s_setprio 1
	s_waitcnt lgkmcnt(0)
	v_mfma_f32_16x16x32_bf16 v[62:65], v[130:133], v[184:187], v[62:65]
	v_mfma_f32_16x16x32_bf16 v[62:65], v[134:137], v[192:195], v[62:65]
	v_mfma_f32_16x16x32_bf16 v[58:61], v[138:141], v[184:187], v[58:61]
	v_mfma_f32_16x16x32_bf16 v[58:61], v[142:145], v[192:195], v[58:61]
	v_mfma_f32_16x16x32_bf16 v[46:49], v[130:133], v[196:199], v[46:49]
	v_mfma_f32_16x16x32_bf16 v[46:49], v[134:137], v[200:203], v[46:49]
	v_mfma_f32_16x16x32_bf16 v[42:45], v[138:141], v[196:199], v[42:45]
	v_mfma_f32_16x16x32_bf16 v[42:45], v[142:145], v[200:203], v[42:45]
	v_mfma_f32_16x16x32_bf16 v[30:33], v[130:133], v[204:207], v[30:33]
	v_mfma_f32_16x16x32_bf16 v[30:33], v[134:137], v[208:211], v[30:33]
	v_mfma_f32_16x16x32_bf16 v[26:29], v[138:141], v[204:207], v[26:29]
	v_mfma_f32_16x16x32_bf16 v[26:29], v[142:145], v[208:211], v[26:29]
	v_mfma_f32_16x16x32_bf16 v[14:17], v[130:133], v[212:215], v[14:17]
	v_mfma_f32_16x16x32_bf16 v[14:17], v[134:137], v[216:219], v[14:17]
	v_mfma_f32_16x16x32_bf16 v[10:13], v[138:141], v[212:215], v[10:13]
	v_mfma_f32_16x16x32_bf16 v[10:13], v[142:145], v[216:219], v[10:13]
	s_setprio 0
	s_setprio 1
	v_mfma_f32_16x16x32_bf16 v[54:57], v[146:149], v[184:187], v[54:57]
	v_mfma_f32_16x16x32_bf16 v[54:57], v[150:153], v[192:195], v[54:57]
	v_mfma_f32_16x16x32_bf16 v[50:53], v[174:177], v[184:187], v[50:53]
	v_mfma_f32_16x16x32_bf16 v[50:53], v[178:181], v[192:195], v[50:53]
	v_mfma_f32_16x16x32_bf16 v[38:41], v[146:149], v[196:199], v[38:41]
	v_mfma_f32_16x16x32_bf16 v[38:41], v[150:153], v[200:203], v[38:41]
	v_mfma_f32_16x16x32_bf16 v[34:37], v[174:177], v[196:199], v[34:37]
	v_mfma_f32_16x16x32_bf16 v[34:37], v[178:181], v[200:203], v[34:37]
	v_mfma_f32_16x16x32_bf16 v[22:25], v[146:149], v[204:207], v[22:25]
	v_mfma_f32_16x16x32_bf16 v[22:25], v[150:153], v[208:211], v[22:25]
	v_mfma_f32_16x16x32_bf16 v[18:21], v[174:177], v[204:207], v[18:21]
	v_mfma_f32_16x16x32_bf16 v[18:21], v[178:181], v[208:211], v[18:21]
	v_mfma_f32_16x16x32_bf16 v[6:9], v[146:149], v[212:215], v[6:9]
	v_mfma_f32_16x16x32_bf16 v[6:9], v[150:153], v[216:219], v[6:9]
	v_mfma_f32_16x16x32_bf16 v[2:5], v[174:177], v[212:215], v[2:5]
	v_mfma_f32_16x16x32_bf16 v[2:5], v[178:181], v[216:219], v[2:5]
	s_setprio 0
	s_barrier
	s_add_i32 s73, s73, 2
	s_add_u32 s46, s46, 0x100
	s_addc_u32 s47, s47, 0
	s_add_u32 s71, s71, 0x100
	s_addc_u32 s72, s72, 0
	s_cmp_gt_u32 s73, 61
	s_cbranch_scc0 .LBB0_2635
	s_and_b64 vcc, exec, s[36:37]
	s_cbranch_vccz .LBB0_2638
	s_barrier

.LBB0_2720:
	ds_read_b128 v[148:151], v159
	ds_read_b128 v[164:167], v159 offset:1024
	ds_read_b128 v[168:171], v159 offset:2048
	ds_read_b128 v[172:175], v159 offset:3072
	ds_read_b128 v[176:179], v160
	ds_read_b128 v[184:187], v160 offset:1024
	ds_read_b128 v[188:191], v160 offset:2048
	ds_read_b128 v[192:195], v160 offset:3072
	s_add_u32 s40, s6, 0xfff00080
	s_addc_u32 s41, s7, -1
	s_cmp_eq_u32 s82, 60
	s_cselect_b32 s43, s29, s41
	s_cselect_b32 s42, s78, s40
	s_cselect_b32 s41, s27, s81
	s_cselect_b32 s40, s79, s80
	s_add_i32 m0, s44, 0xc000
	ds_read_b128 v[196:199], v161
	ds_read_b128 v[200:203], v161 offset:1024
	ds_read_b128 v[204:207], v161 offset:2048
	ds_read_b128 v[208:211], v161 offset:3072
	ds_read_b128 v[212:215], v161 offset:4096
	ds_read_b128 v[216:219], v161 offset:5120
	ds_read_b128 v[220:223], v161 offset:6144
	ds_read_b128 v[224:227], v161 offset:7168
	global_load_lds_dwordx4 v140, s[6:7]
	s_add_i32 m0, s44, 0xe000
	s_nop 0
	global_load_lds_dwordx4 v142, s[6:7]
	s_waitcnt vmcnt(8)
	s_waitcnt lgkmcnt(0)
	s_barrier
	s_setprio 1
	s_waitcnt lgkmcnt(0)
	v_mfma_f32_16x16x32_bf16 v[126:129], v[148:151], v[196:199], v[126:129]
	v_mfma_f32_16x16x32_bf16 v[126:129], v[164:167], v[200:203], v[126:129]
	v_mfma_f32_16x16x32_bf16 v[118:121], v[168:171], v[196:199], v[118:121]
	v_mfma_f32_16x16x32_bf16 v[118:121], v[172:175], v[200:203], v[118:121]
	v_mfma_f32_16x16x32_bf16 v[110:113], v[148:151], v[204:207], v[110:113]
	v_mfma_f32_16x16x32_bf16 v[110:113], v[164:167], v[208:211], v[110:113]
	v_mfma_f32_16x16x32_bf16 v[102:105], v[168:171], v[204:207], v[102:105]
	v_mfma_f32_16x16x32_bf16 v[102:105], v[172:175], v[208:211], v[102:105]
	v_mfma_f32_16x16x32_bf16 v[94:97], v[148:151], v[212:215], v[94:97]
	v_mfma_f32_16x16x32_bf16 v[94:97], v[164:167], v[216:219], v[94:97]
	v_mfma_f32_16x16x32_bf16 v[86:89], v[168:171], v[212:215], v[86:89]
	v_mfma_f32_16x16x32_bf16 v[86:89], v[172:175], v[216:219], v[86:89]
	v_mfma_f32_16x16x32_bf16 v[78:81], v[148:151], v[220:223], v[78:81]
	v_mfma_f32_16x16x32_bf16 v[78:81], v[164:167], v[224:227], v[78:81]
	v_mfma_f32_16x16x32_bf16 v[70:73], v[168:171], v[220:223], v[70:73]
	v_mfma_f32_16x16x32_bf16 v[70:73], v[172:175], v[224:227], v[70:73]
	s_setprio 0
	s_setprio 1
	v_mfma_f32_16x16x32_bf16 v[122:125], v[176:179], v[196:199], v[122:125]
	v_mfma_f32_16x16x32_bf16 v[122:125], v[184:187], v[200:203], v[122:125]
	v_mfma_f32_16x16x32_bf16 v[114:117], v[188:191], v[196:199], v[114:117]
	v_mfma_f32_16x16x32_bf16 v[114:117], v[192:195], v[200:203], v[114:117]
	v_mfma_f32_16x16x32_bf16 v[106:109], v[176:179], v[204:207], v[106:109]
	v_mfma_f32_16x16x32_bf16 v[106:109], v[184:187], v[208:211], v[106:109]
	v_mfma_f32_16x16x32_bf16 v[98:101], v[188:191], v[204:207], v[98:101]
	v_mfma_f32_16x16x32_bf16 v[98:101], v[192:195], v[208:211], v[98:101]
	v_mfma_f32_16x16x32_bf16 v[90:93], v[176:179], v[212:215], v[90:93]
	v_mfma_f32_16x16x32_bf16 v[90:93], v[184:187], v[216:219], v[90:93]
	v_mfma_f32_16x16x32_bf16 v[82:85], v[188:191], v[212:215], v[82:85]
	v_mfma_f32_16x16x32_bf16 v[82:85], v[192:195], v[216:219], v[82:85]
	v_mfma_f32_16x16x32_bf16 v[74:77], v[176:179], v[220:223], v[74:77]
	v_mfma_f32_16x16x32_bf16 v[74:77], v[184:187], v[224:227], v[74:77]
	v_mfma_f32_16x16x32_bf16 v[66:69], v[188:191], v[220:223], v[66:69]
	v_mfma_f32_16x16x32_bf16 v[66:69], v[192:195], v[224:227], v[66:69]
	s_setprio 0
	s_barrier
	s_add_i32 s83, s68, s13
	s_add_u32 s98, s40, 0x80
	s_addc_u32 s99, s41, 0
	s_mov_b32 m0, s83
	ds_read_b128 v[196:199], v161 offset:16384
	ds_read_b128 v[200:203], v161 offset:17408
	ds_read_b128 v[204:207], v161 offset:18432
	ds_read_b128 v[208:211], v161 offset:19456
	ds_read_b128 v[212:215], v161 offset:20480
	ds_read_b128 v[216:219], v161 offset:21504
	ds_read_b128 v[220:223], v161 offset:22528
	ds_read_b128 v[224:227], v161 offset:23552
	global_load_lds_dwordx4 v132, s[40:41]
	s_add_i32 m0, s83, 0x2000
	s_add_u32 s84, s40, 0x100000
	s_addc_u32 s85, s41, 0
	s_add_i32 s83, s69, s13
	global_load_lds_dwordx4 v136, s[40:41]
	s_mov_b32 m0, s83
	global_load_lds_dwordx4 v132, s[84:85]
	s_add_i32 m0, s83, 0x2000
	s_nop 0
	global_load_lds_dwordx4 v136, s[84:85]
	s_add_u32 s100, s42, 0x80
	s_addc_u32 s101, s43, 0
	s_mov_b32 m0, s44
	s_nop 0
	global_load_lds_dwordx4 v130, s[42:43]
	s_mov_b32 m0, s45
	s_nop 0
	global_load_lds_dwordx4 v134, s[42:43]
	s_waitcnt vmcnt(8)
	s_waitcnt lgkmcnt(0)
	s_barrier
	s_setprio 1
	s_waitcnt lgkmcnt(0)
	v_mfma_f32_16x16x32_bf16 v[62:65], v[148:151], v[196:199], v[62:65]
	v_mfma_f32_16x16x32_bf16 v[62:65], v[164:167], v[200:203], v[62:65]
	v_mfma_f32_16x16x32_bf16 v[54:57], v[168:171], v[196:199], v[54:57]
	v_mfma_f32_16x16x32_bf16 v[54:57], v[172:175], v[200:203], v[54:57]
	v_mfma_f32_16x16x32_bf16 v[46:49], v[148:151], v[204:207], v[46:49]
	v_mfma_f32_16x16x32_bf16 v[46:49], v[164:167], v[208:211], v[46:49]
	v_mfma_f32_16x16x32_bf16 v[38:41], v[168:171], v[204:207], v[38:41]
	v_mfma_f32_16x16x32_bf16 v[38:41], v[172:175], v[208:211], v[38:41]
	v_mfma_f32_16x16x32_bf16 v[30:33], v[148:151], v[212:215], v[30:33]
	v_mfma_f32_16x16x32_bf16 v[30:33], v[164:167], v[216:219], v[30:33]
	v_mfma_f32_16x16x32_bf16 v[22:25], v[168:171], v[212:215], v[22:25]
	v_mfma_f32_16x16x32_bf16 v[22:25], v[172:175], v[216:219], v[22:25]
	v_mfma_f32_16x16x32_bf16 v[14:17], v[148:151], v[220:223], v[14:17]
	v_mfma_f32_16x16x32_bf16 v[14:17], v[164:167], v[224:227], v[14:17]
	v_mfma_f32_16x16x32_bf16 v[6:9], v[168:171], v[220:223], v[6:9]
	v_mfma_f32_16x16x32_bf16 v[6:9], v[172:175], v[224:227], v[6:9]
	s_setprio 0
	s_setprio 1
	v_mfma_f32_16x16x32_bf16 v[58:61], v[176:179], v[196:199], v[58:61]
	v_mfma_f32_16x16x32_bf16 v[58:61], v[184:187], v[200:203], v[58:61]
	v_mfma_f32_16x16x32_bf16 v[50:53], v[188:191], v[196:199], v[50:53]
	v_mfma_f32_16x16x32_bf16 v[50:53], v[192:195], v[200:203], v[50:53]
	v_mfma_f32_16x16x32_bf16 v[42:45], v[176:179], v[204:207], v[42:45]
	v_mfma_f32_16x16x32_bf16 v[42:45], v[184:187], v[208:211], v[42:45]
	v_mfma_f32_16x16x32_bf16 v[34:37], v[188:191], v[204:207], v[34:37]
	v_mfma_f32_16x16x32_bf16 v[34:37], v[192:195], v[208:211], v[34:37]
	v_mfma_f32_16x16x32_bf16 v[26:29], v[176:179], v[212:215], v[26:29]
	v_mfma_f32_16x16x32_bf16 v[26:29], v[184:187], v[216:219], v[26:29]
	v_mfma_f32_16x16x32_bf16 v[18:21], v[188:191], v[212:215], v[18:21]
	v_mfma_f32_16x16x32_bf16 v[18:21], v[192:195], v[216:219], v[18:21]
	v_mfma_f32_16x16x32_bf16 v[10:13], v[176:179], v[220:223], v[10:13]
	v_mfma_f32_16x16x32_bf16 v[10:13], v[184:187], v[224:227], v[10:13]
	v_mfma_f32_16x16x32_bf16 v[2:5], v[188:191], v[220:223], v[2:5]
	v_mfma_f32_16x16x32_bf16 v[2:5], v[192:195], v[224:227], v[2:5]
	s_setprio 0
	s_barrier
	s_add_i32 s83, 0, 0x18000
	v_add_u32_e32 v138, s83, v155
	s_add_i32 s84, 0, 0x1c000
	ds_read_b128 v[148:151], v138
	ds_read_b128 v[164:167], v138 offset:1024
	ds_read_b128 v[168:171], v138 offset:2048
	ds_read_b128 v[172:175], v138 offset:3072
	v_add_u32_e32 v138, s84, v155
	ds_read_b128 v[176:179], v138
	ds_read_b128 v[184:187], v138 offset:1024
	ds_read_b128 v[188:191], v138 offset:2048
	ds_read_b128 v[192:195], v138 offset:3072
	s_add_u32 s42, s42, 0x100000
	s_addc_u32 s43, s43, 0
	s_mov_b32 m0, s46
	ds_read_b128 v[196:199], v161 offset:32768
	ds_read_b128 v[200:203], v161 offset:33792
	ds_read_b128 v[204:207], v161 offset:34816
	ds_read_b128 v[208:211], v161 offset:35840
	ds_read_b128 v[212:215], v161 offset:36864
	ds_read_b128 v[216:219], v161 offset:37888
	ds_read_b128 v[220:223], v161 offset:38912
	ds_read_b128 v[224:227], v161 offset:39936
	global_load_lds_dwordx4 v130, s[42:43]
	s_mov_b32 m0, s47
	s_nop 0
	global_load_lds_dwordx4 v134, s[42:43]
	s_waitcnt vmcnt(8)
	s_waitcnt lgkmcnt(0)
	s_barrier
	s_setprio 1
	s_waitcnt lgkmcnt(0)
	v_mfma_f32_16x16x32_bf16 v[126:129], v[148:151], v[196:199], v[126:129]
	v_mfma_f32_16x16x32_bf16 v[126:129], v[164:167], v[200:203], v[126:129]
	v_mfma_f32_16x16x32_bf16 v[118:121], v[168:171], v[196:199], v[118:121]
	v_mfma_f32_16x16x32_bf16 v[118:121], v[172:175], v[200:203], v[118:121]
	v_mfma_f32_16x16x32_bf16 v[110:113], v[148:151], v[204:207], v[110:113]
	v_mfma_f32_16x16x32_bf16 v[110:113], v[164:167], v[208:211], v[110:113]
	v_mfma_f32_16x16x32_bf16 v[102:105], v[168:171], v[204:207], v[102:105]
	v_mfma_f32_16x16x32_bf16 v[102:105], v[172:175], v[208:211], v[102:105]
	v_mfma_f32_16x16x32_bf16 v[94:97], v[148:151], v[212:215], v[94:97]
	v_mfma_f32_16x16x32_bf16 v[94:97], v[164:167], v[216:219], v[94:97]
	v_mfma_f32_16x16x32_bf16 v[86:89], v[168:171], v[212:215], v[86:89]
	v_mfma_f32_16x16x32_bf16 v[86:89], v[172:175], v[216:219], v[86:89]
	v_mfma_f32_16x16x32_bf16 v[78:81], v[148:151], v[220:223], v[78:81]
	v_mfma_f32_16x16x32_bf16 v[78:81], v[164:167], v[224:227], v[78:81]
	v_mfma_f32_16x16x32_bf16 v[70:73], v[168:171], v[220:223], v[70:73]
	v_mfma_f32_16x16x32_bf16 v[70:73], v[172:175], v[224:227], v[70:73]
	s_setprio 0
	s_setprio 1
	v_mfma_f32_16x16x32_bf16 v[122:125], v[176:179], v[196:199], v[122:125]
	v_mfma_f32_16x16x32_bf16 v[122:125], v[184:187], v[200:203], v[122:125]
	v_mfma_f32_16x16x32_bf16 v[114:117], v[188:191], v[196:199], v[114:117]
	v_mfma_f32_16x16x32_bf16 v[114:117], v[192:195], v[200:203], v[114:117]
	v_mfma_f32_16x16x32_bf16 v[106:109], v[176:179], v[204:207], v[106:109]
	v_mfma_f32_16x16x32_bf16 v[106:109], v[184:187], v[208:211], v[106:109]
	v_mfma_f32_16x16x32_bf16 v[98:101], v[188:191], v[204:207], v[98:101]
	v_mfma_f32_16x16x32_bf16 v[98:101], v[192:195], v[208:211], v[98:101]
	v_mfma_f32_16x16x32_bf16 v[90:93], v[176:179], v[212:215], v[90:93]
	v_mfma_f32_16x16x32_bf16 v[90:93], v[184:187], v[216:219], v[90:93]
	v_mfma_f32_16x16x32_bf16 v[82:85], v[188:191], v[212:215], v[82:85]
	v_mfma_f32_16x16x32_bf16 v[82:85], v[192:195], v[216:219], v[82:85]
	v_mfma_f32_16x16x32_bf16 v[74:77], v[176:179], v[220:223], v[74:77]
	v_mfma_f32_16x16x32_bf16 v[74:77], v[184:187], v[224:227], v[74:77]
	v_mfma_f32_16x16x32_bf16 v[66:69], v[188:191], v[220:223], v[66:69]
	v_mfma_f32_16x16x32_bf16 v[66:69], v[192:195], v[224:227], v[66:69]
	s_setprio 0
	s_barrier
	s_add_i32 s42, s83, s13
	s_mov_b32 m0, s42
	ds_read_b128 v[196:199], v161 offset:49152
	ds_read_b128 v[200:203], v161 offset:50176
	ds_read_b128 v[204:207], v161 offset:51200
	ds_read_b128 v[208:211], v161 offset:52224
	ds_read_b128 v[212:215], v161 offset:53248
	ds_read_b128 v[216:219], v161 offset:54272
	ds_read_b128 v[220:223], v161 offset:55296
	ds_read_b128 v[224:227], v161 offset:56320
	global_load_lds_dwordx4 v132, s[98:99]
	s_add_i32 m0, s42, 0x2000
	s_add_u32 s40, s40, 0x100080
	s_addc_u32 s41, s41, 0
	s_add_i32 s42, s84, s13
	global_load_lds_dwordx4 v136, s[98:99]
	s_mov_b32 m0, s42
	s_nop 0
	global_load_lds_dwordx4 v132, s[40:41]
	s_add_i32 m0, s42, 0x2000
	s_nop 0
	global_load_lds_dwordx4 v136, s[40:41]
	s_mov_b32 m0, s59
	s_nop 0
	global_load_lds_dwordx4 v130, s[100:101]
	s_mov_b32 m0, s62
	s_nop 0
	global_load_lds_dwordx4 v134, s[100:101]
	s_waitcnt vmcnt(8)
	s_waitcnt lgkmcnt(0)
	s_barrier
	s_setprio 1
	s_waitcnt lgkmcnt(0)
	v_mfma_f32_16x16x32_bf16 v[62:65], v[148:151], v[196:199], v[62:65]
	v_mfma_f32_16x16x32_bf16 v[62:65], v[164:167], v[200:203], v[62:65]
	v_mfma_f32_16x16x32_bf16 v[54:57], v[168:171], v[196:199], v[54:57]
	v_mfma_f32_16x16x32_bf16 v[54:57], v[172:175], v[200:203], v[54:57]
	v_mfma_f32_16x16x32_bf16 v[46:49], v[148:151], v[204:207], v[46:49]
	v_mfma_f32_16x16x32_bf16 v[46:49], v[164:167], v[208:211], v[46:49]
	v_mfma_f32_16x16x32_bf16 v[38:41], v[168:171], v[204:207], v[38:41]
	v_mfma_f32_16x16x32_bf16 v[38:41], v[172:175], v[208:211], v[38:41]
	v_mfma_f32_16x16x32_bf16 v[30:33], v[148:151], v[212:215], v[30:33]
	v_mfma_f32_16x16x32_bf16 v[30:33], v[164:167], v[216:219], v[30:33]
	v_mfma_f32_16x16x32_bf16 v[22:25], v[168:171], v[212:215], v[22:25]
	v_mfma_f32_16x16x32_bf16 v[22:25], v[172:175], v[216:219], v[22:25]
	v_mfma_f32_16x16x32_bf16 v[14:17], v[148:151], v[220:223], v[14:17]
	v_mfma_f32_16x16x32_bf16 v[14:17], v[164:167], v[224:227], v[14:17]
	v_mfma_f32_16x16x32_bf16 v[6:9], v[168:171], v[220:223], v[6:9]
	v_mfma_f32_16x16x32_bf16 v[6:9], v[172:175], v[224:227], v[6:9]
	s_setprio 0
	s_setprio 1
	v_mfma_f32_16x16x32_bf16 v[58:61], v[176:179], v[196:199], v[58:61]
	v_mfma_f32_16x16x32_bf16 v[58:61], v[184:187], v[200:203], v[58:61]
	v_mfma_f32_16x16x32_bf16 v[50:53], v[188:191], v[196:199], v[50:53]
	v_mfma_f32_16x16x32_bf16 v[50:53], v[192:195], v[200:203], v[50:53]
	v_mfma_f32_16x16x32_bf16 v[42:45], v[176:179], v[204:207], v[42:45]
	v_mfma_f32_16x16x32_bf16 v[42:45], v[184:187], v[208:211], v[42:45]
	v_mfma_f32_16x16x32_bf16 v[34:37], v[188:191], v[204:207], v[34:37]
	v_mfma_f32_16x16x32_bf16 v[34:37], v[192:195], v[208:211], v[34:37]
	v_mfma_f32_16x16x32_bf16 v[26:29], v[176:179], v[212:215], v[26:29]
	v_mfma_f32_16x16x32_bf16 v[26:29], v[184:187], v[216:219], v[26:29]
	v_mfma_f32_16x16x32_bf16 v[18:21], v[188:191], v[212:215], v[18:21]
	v_mfma_f32_16x16x32_bf16 v[18:21], v[192:195], v[216:219], v[18:21]
	v_mfma_f32_16x16x32_bf16 v[10:13], v[176:179], v[220:223], v[10:13]
	v_mfma_f32_16x16x32_bf16 v[10:13], v[184:187], v[224:227], v[10:13]
	v_mfma_f32_16x16x32_bf16 v[2:5], v[188:191], v[220:223], v[2:5]
	v_mfma_f32_16x16x32_bf16 v[2:5], v[192:195], v[224:227], v[2:5]
	s_setprio 0
	s_barrier
	s_add_i32 s82, s82, 2
	s_add_u32 s6, s6, 0x100
	s_addc_u32 s7, s7, 0
	s_add_u32 s80, s80, 0x100
	s_addc_u32 s81, s81, 0
	s_cmp_gt_u32 s82, 61
	s_cbranch_scc0 .LBB0_2720
	s_and_b64 vcc, exec, s[24:25]
	s_cbranch_vccz .LBB0_2723
	s_barrier

.LBB0_2805:
	ds_read_b128 v[130:133], v163
	ds_read_b128 v[134:137], v163 offset:1024
	ds_read_b128 v[138:141], v163 offset:2048
	ds_read_b128 v[142:145], v163 offset:3072
	ds_read_b128 v[146:149], v188
	ds_read_b128 v[150:153], v188 offset:1024
	ds_read_b128 v[174:177], v188 offset:2048
	ds_read_b128 v[178:181], v188 offset:3072
	s_add_u32 s28, s26, 0xffd50080
	s_addc_u32 s29, s27, -1
	s_cmpk_eq_i32 s62, 0xa8
	s_cselect_b32 s37, s7, s29
	s_cselect_b32 s36, s6, s28
	s_cselect_b32 s29, s25, s59
	s_cselect_b32 s28, s24, s12
	s_add_i32 m0, s38, 0xc000
	ds_read_b128 v[184:187], v189
	ds_read_b128 v[192:195], v189 offset:1024
	ds_read_b128 v[196:199], v189 offset:2048
	ds_read_b128 v[200:203], v189 offset:3072
	ds_read_b128 v[204:207], v189 offset:4096
	ds_read_b128 v[208:211], v189 offset:5120
	ds_read_b128 v[212:215], v189 offset:6144
	ds_read_b128 v[216:219], v189 offset:7168
	global_load_lds_dwordx4 v166, s[26:27]
	s_add_i32 m0, s38, 0xe000
	s_nop 0
	global_load_lds_dwordx4 v168, s[26:27]
	s_waitcnt vmcnt(8)
	s_waitcnt lgkmcnt(0)
	s_barrier
	s_setprio 1
	s_waitcnt lgkmcnt(0)
	v_mfma_f32_16x16x32_bf16 v[126:129], v[130:133], v[184:187], v[126:129]
	v_mfma_f32_16x16x32_bf16 v[126:129], v[134:137], v[192:195], v[126:129]
	v_mfma_f32_16x16x32_bf16 v[122:125], v[138:141], v[184:187], v[122:125]
	v_mfma_f32_16x16x32_bf16 v[122:125], v[142:145], v[192:195], v[122:125]
	v_mfma_f32_16x16x32_bf16 v[110:113], v[130:133], v[196:199], v[110:113]
	v_mfma_f32_16x16x32_bf16 v[110:113], v[134:137], v[200:203], v[110:113]
	v_mfma_f32_16x16x32_bf16 v[106:109], v[138:141], v[196:199], v[106:109]
	v_mfma_f32_16x16x32_bf16 v[106:109], v[142:145], v[200:203], v[106:109]
	v_mfma_f32_16x16x32_bf16 v[94:97], v[130:133], v[204:207], v[94:97]
	v_mfma_f32_16x16x32_bf16 v[94:97], v[134:137], v[208:211], v[94:97]
	v_mfma_f32_16x16x32_bf16 v[90:93], v[138:141], v[204:207], v[90:93]
	v_mfma_f32_16x16x32_bf16 v[90:93], v[142:145], v[208:211], v[90:93]
	v_mfma_f32_16x16x32_bf16 v[78:81], v[130:133], v[212:215], v[78:81]
	v_mfma_f32_16x16x32_bf16 v[78:81], v[134:137], v[216:219], v[78:81]
	v_mfma_f32_16x16x32_bf16 v[74:77], v[138:141], v[212:215], v[74:77]
	v_mfma_f32_16x16x32_bf16 v[74:77], v[142:145], v[216:219], v[74:77]
	s_setprio 0
	s_setprio 1
	v_mfma_f32_16x16x32_bf16 v[118:121], v[146:149], v[184:187], v[118:121]
	v_mfma_f32_16x16x32_bf16 v[118:121], v[150:153], v[192:195], v[118:121]
	v_mfma_f32_16x16x32_bf16 v[114:117], v[174:177], v[184:187], v[114:117]
	v_mfma_f32_16x16x32_bf16 v[114:117], v[178:181], v[192:195], v[114:117]
	v_mfma_f32_16x16x32_bf16 v[102:105], v[146:149], v[196:199], v[102:105]
	v_mfma_f32_16x16x32_bf16 v[102:105], v[150:153], v[200:203], v[102:105]
	v_mfma_f32_16x16x32_bf16 v[98:101], v[174:177], v[196:199], v[98:101]
	v_mfma_f32_16x16x32_bf16 v[98:101], v[178:181], v[200:203], v[98:101]
	v_mfma_f32_16x16x32_bf16 v[86:89], v[146:149], v[204:207], v[86:89]
	v_mfma_f32_16x16x32_bf16 v[86:89], v[150:153], v[208:211], v[86:89]
	v_mfma_f32_16x16x32_bf16 v[82:85], v[174:177], v[204:207], v[82:85]
	v_mfma_f32_16x16x32_bf16 v[82:85], v[178:181], v[208:211], v[82:85]
	v_mfma_f32_16x16x32_bf16 v[70:73], v[146:149], v[212:215], v[70:73]
	v_mfma_f32_16x16x32_bf16 v[70:73], v[150:153], v[216:219], v[70:73]
	v_mfma_f32_16x16x32_bf16 v[66:69], v[174:177], v[212:215], v[66:69]
	v_mfma_f32_16x16x32_bf16 v[66:69], v[178:181], v[216:219], v[66:69]
	s_setprio 0
	s_barrier
	s_add_i32 s63, s47, s35
	s_add_u32 s98, s28, 0x80
	s_addc_u32 s99, s29, 0
	s_mov_b32 m0, s63
	ds_read_b128 v[184:187], v189 offset:16384
	ds_read_b128 v[192:195], v189 offset:17408
	ds_read_b128 v[196:199], v189 offset:18432
	ds_read_b128 v[200:203], v189 offset:19456
	ds_read_b128 v[204:207], v189 offset:20480
	ds_read_b128 v[208:211], v189 offset:21504
	ds_read_b128 v[212:215], v189 offset:22528
	ds_read_b128 v[216:219], v189 offset:23552
	global_load_lds_dwordx4 v156, s[28:29]
	s_add_i32 m0, s63, 0x2000
	s_add_u32 s66, s28, 0x2b0000
	s_addc_u32 s67, s29, 0
	s_add_i32 s63, s48, s35
	global_load_lds_dwordx4 v160, s[28:29]
	s_mov_b32 m0, s63
	global_load_lds_dwordx4 v156, s[66:67]
	s_add_i32 m0, s63, 0x2000
	s_nop 0
	global_load_lds_dwordx4 v160, s[66:67]
	s_add_u32 s100, s36, 0x80
	s_addc_u32 s101, s37, 0
	s_mov_b32 m0, s38
	s_nop 0
	global_load_lds_dwordx4 v154, s[36:37]
	s_mov_b32 m0, s39
	s_nop 0
	global_load_lds_dwordx4 v158, s[36:37]
	s_waitcnt vmcnt(8)
	s_waitcnt lgkmcnt(0)
	s_barrier
	s_setprio 1
	s_waitcnt lgkmcnt(0)
	v_mfma_f32_16x16x32_bf16 v[62:65], v[130:133], v[184:187], v[62:65]
	v_mfma_f32_16x16x32_bf16 v[62:65], v[134:137], v[192:195], v[62:65]
	v_mfma_f32_16x16x32_bf16 v[58:61], v[138:141], v[184:187], v[58:61]
	v_mfma_f32_16x16x32_bf16 v[58:61], v[142:145], v[192:195], v[58:61]
	v_mfma_f32_16x16x32_bf16 v[46:49], v[130:133], v[196:199], v[46:49]
	v_mfma_f32_16x16x32_bf16 v[46:49], v[134:137], v[200:203], v[46:49]
	v_mfma_f32_16x16x32_bf16 v[42:45], v[138:141], v[196:199], v[42:45]
	v_mfma_f32_16x16x32_bf16 v[42:45], v[142:145], v[200:203], v[42:45]
	v_mfma_f32_16x16x32_bf16 v[30:33], v[130:133], v[204:207], v[30:33]
	v_mfma_f32_16x16x32_bf16 v[30:33], v[134:137], v[208:211], v[30:33]
	v_mfma_f32_16x16x32_bf16 v[26:29], v[138:141], v[204:207], v[26:29]
	v_mfma_f32_16x16x32_bf16 v[26:29], v[142:145], v[208:211], v[26:29]
	v_mfma_f32_16x16x32_bf16 v[14:17], v[130:133], v[212:215], v[14:17]
	v_mfma_f32_16x16x32_bf16 v[14:17], v[134:137], v[216:219], v[14:17]
	v_mfma_f32_16x16x32_bf16 v[10:13], v[138:141], v[212:215], v[10:13]
	v_mfma_f32_16x16x32_bf16 v[10:13], v[142:145], v[216:219], v[10:13]
	s_setprio 0
	s_setprio 1
	v_mfma_f32_16x16x32_bf16 v[54:57], v[146:149], v[184:187], v[54:57]
	v_mfma_f32_16x16x32_bf16 v[54:57], v[150:153], v[192:195], v[54:57]
	v_mfma_f32_16x16x32_bf16 v[50:53], v[174:177], v[184:187], v[50:53]
	v_mfma_f32_16x16x32_bf16 v[50:53], v[178:181], v[192:195], v[50:53]
	v_mfma_f32_16x16x32_bf16 v[38:41], v[146:149], v[196:199], v[38:41]
	v_mfma_f32_16x16x32_bf16 v[38:41], v[150:153], v[200:203], v[38:41]
	v_mfma_f32_16x16x32_bf16 v[34:37], v[174:177], v[196:199], v[34:37]
	v_mfma_f32_16x16x32_bf16 v[34:37], v[178:181], v[200:203], v[34:37]
	v_mfma_f32_16x16x32_bf16 v[22:25], v[146:149], v[204:207], v[22:25]
	v_mfma_f32_16x16x32_bf16 v[22:25], v[150:153], v[208:211], v[22:25]
	v_mfma_f32_16x16x32_bf16 v[18:21], v[174:177], v[204:207], v[18:21]
	v_mfma_f32_16x16x32_bf16 v[18:21], v[178:181], v[208:211], v[18:21]
	v_mfma_f32_16x16x32_bf16 v[6:9], v[146:149], v[212:215], v[6:9]
	v_mfma_f32_16x16x32_bf16 v[6:9], v[150:153], v[216:219], v[6:9]
	v_mfma_f32_16x16x32_bf16 v[2:5], v[174:177], v[212:215], v[2:5]
	v_mfma_f32_16x16x32_bf16 v[2:5], v[178:181], v[216:219], v[2:5]
	s_setprio 0
	s_barrier
	s_add_i32 s63, 0, 0x18000
	s_add_i32 s65, 0, 0x1c000
	v_add_u32_e32 v142, s63, v1
	v_add_u32_e32 v178, s65, v1
	ds_read_b128 v[130:133], v142
	ds_read_b128 v[134:137], v142 offset:1024
	ds_read_b128 v[138:141], v142 offset:2048
	ds_read_b128 v[142:145], v142 offset:3072
	ds_read_b128 v[146:149], v178
	ds_read_b128 v[150:153], v178 offset:1024
	ds_read_b128 v[174:177], v178 offset:2048
	ds_read_b128 v[178:181], v178 offset:3072
	s_add_u32 s36, s36, 0x2b0000
	s_addc_u32 s37, s37, 0
	s_mov_b32 m0, s40
	ds_read_b128 v[184:187], v189 offset:32768
	ds_read_b128 v[192:195], v189 offset:33792
	ds_read_b128 v[196:199], v189 offset:34816
	ds_read_b128 v[200:203], v189 offset:35840
	ds_read_b128 v[204:207], v189 offset:36864
	ds_read_b128 v[208:211], v189 offset:37888
	ds_read_b128 v[212:215], v189 offset:38912
	ds_read_b128 v[216:219], v189 offset:39936
	global_load_lds_dwordx4 v154, s[36:37]
	s_mov_b32 m0, s41
	s_nop 0
	global_load_lds_dwordx4 v158, s[36:37]
	s_waitcnt vmcnt(8)
	s_waitcnt lgkmcnt(0)
	s_barrier
	s_setprio 1
	s_waitcnt lgkmcnt(0)
	v_mfma_f32_16x16x32_bf16 v[126:129], v[130:133], v[184:187], v[126:129]
	v_mfma_f32_16x16x32_bf16 v[126:129], v[134:137], v[192:195], v[126:129]
	v_mfma_f32_16x16x32_bf16 v[122:125], v[138:141], v[184:187], v[122:125]
	v_mfma_f32_16x16x32_bf16 v[122:125], v[142:145], v[192:195], v[122:125]
	v_mfma_f32_16x16x32_bf16 v[110:113], v[130:133], v[196:199], v[110:113]
	v_mfma_f32_16x16x32_bf16 v[110:113], v[134:137], v[200:203], v[110:113]
	v_mfma_f32_16x16x32_bf16 v[106:109], v[138:141], v[196:199], v[106:109]
	v_mfma_f32_16x16x32_bf16 v[106:109], v[142:145], v[200:203], v[106:109]
	v_mfma_f32_16x16x32_bf16 v[94:97], v[130:133], v[204:207], v[94:97]
	v_mfma_f32_16x16x32_bf16 v[94:97], v[134:137], v[208:211], v[94:97]
	v_mfma_f32_16x16x32_bf16 v[90:93], v[138:141], v[204:207], v[90:93]
	v_mfma_f32_16x16x32_bf16 v[90:93], v[142:145], v[208:211], v[90:93]
	v_mfma_f32_16x16x32_bf16 v[78:81], v[130:133], v[212:215], v[78:81]
	v_mfma_f32_16x16x32_bf16 v[78:81], v[134:137], v[216:219], v[78:81]
	v_mfma_f32_16x16x32_bf16 v[74:77], v[138:141], v[212:215], v[74:77]
	v_mfma_f32_16x16x32_bf16 v[74:77], v[142:145], v[216:219], v[74:77]
	s_setprio 0
	s_setprio 1
	v_mfma_f32_16x16x32_bf16 v[118:121], v[146:149], v[184:187], v[118:121]
	v_mfma_f32_16x16x32_bf16 v[118:121], v[150:153], v[192:195], v[118:121]
	v_mfma_f32_16x16x32_bf16 v[114:117], v[174:177], v[184:187], v[114:117]
	v_mfma_f32_16x16x32_bf16 v[114:117], v[178:181], v[192:195], v[114:117]
	v_mfma_f32_16x16x32_bf16 v[102:105], v[146:149], v[196:199], v[102:105]
	v_mfma_f32_16x16x32_bf16 v[102:105], v[150:153], v[200:203], v[102:105]
	v_mfma_f32_16x16x32_bf16 v[98:101], v[174:177], v[196:199], v[98:101]
	v_mfma_f32_16x16x32_bf16 v[98:101], v[178:181], v[200:203], v[98:101]
	v_mfma_f32_16x16x32_bf16 v[86:89], v[146:149], v[204:207], v[86:89]
	v_mfma_f32_16x16x32_bf16 v[86:89], v[150:153], v[208:211], v[86:89]
	v_mfma_f32_16x16x32_bf16 v[82:85], v[174:177], v[204:207], v[82:85]
	v_mfma_f32_16x16x32_bf16 v[82:85], v[178:181], v[208:211], v[82:85]
	v_mfma_f32_16x16x32_bf16 v[70:73], v[146:149], v[212:215], v[70:73]
	v_mfma_f32_16x16x32_bf16 v[70:73], v[150:153], v[216:219], v[70:73]
	v_mfma_f32_16x16x32_bf16 v[66:69], v[174:177], v[212:215], v[66:69]
	v_mfma_f32_16x16x32_bf16 v[66:69], v[178:181], v[216:219], v[66:69]
	s_setprio 0
	s_barrier
	s_add_i32 s36, s63, s35
	s_mov_b32 m0, s36
	ds_read_b128 v[184:187], v189 offset:49152
	ds_read_b128 v[192:195], v189 offset:50176
	ds_read_b128 v[196:199], v189 offset:51200
	ds_read_b128 v[200:203], v189 offset:52224
	ds_read_b128 v[204:207], v189 offset:53248
	ds_read_b128 v[208:211], v189 offset:54272
	ds_read_b128 v[212:215], v189 offset:55296
	ds_read_b128 v[216:219], v189 offset:56320
	global_load_lds_dwordx4 v156, s[98:99]
	s_add_i32 m0, s36, 0x2000
	s_add_u32 s28, s28, 0x2b0080
	s_addc_u32 s29, s29, 0
	s_add_i32 s36, s65, s35
	global_load_lds_dwordx4 v160, s[98:99]
	s_mov_b32 m0, s36
	s_nop 0
	global_load_lds_dwordx4 v156, s[28:29]
	s_add_i32 m0, s36, 0x2000
	s_nop 0
	global_load_lds_dwordx4 v160, s[28:29]
	s_mov_b32 m0, s43
	s_nop 0
	global_load_lds_dwordx4 v154, s[100:101]
	s_mov_b32 m0, s44
	s_nop 0
	global_load_lds_dwordx4 v158, s[100:101]
	s_waitcnt vmcnt(8)
	s_waitcnt lgkmcnt(0)
	s_barrier
	s_setprio 1
	s_waitcnt lgkmcnt(0)
	v_mfma_f32_16x16x32_bf16 v[62:65], v[130:133], v[184:187], v[62:65]
	v_mfma_f32_16x16x32_bf16 v[62:65], v[134:137], v[192:195], v[62:65]
	v_mfma_f32_16x16x32_bf16 v[58:61], v[138:141], v[184:187], v[58:61]
	v_mfma_f32_16x16x32_bf16 v[58:61], v[142:145], v[192:195], v[58:61]
	v_mfma_f32_16x16x32_bf16 v[46:49], v[130:133], v[196:199], v[46:49]
	v_mfma_f32_16x16x32_bf16 v[46:49], v[134:137], v[200:203], v[46:49]
	v_mfma_f32_16x16x32_bf16 v[42:45], v[138:141], v[196:199], v[42:45]
	v_mfma_f32_16x16x32_bf16 v[42:45], v[142:145], v[200:203], v[42:45]
	v_mfma_f32_16x16x32_bf16 v[30:33], v[130:133], v[204:207], v[30:33]
	v_mfma_f32_16x16x32_bf16 v[30:33], v[134:137], v[208:211], v[30:33]
	v_mfma_f32_16x16x32_bf16 v[26:29], v[138:141], v[204:207], v[26:29]
	v_mfma_f32_16x16x32_bf16 v[26:29], v[142:145], v[208:211], v[26:29]
	v_mfma_f32_16x16x32_bf16 v[14:17], v[130:133], v[212:215], v[14:17]
	v_mfma_f32_16x16x32_bf16 v[14:17], v[134:137], v[216:219], v[14:17]
	v_mfma_f32_16x16x32_bf16 v[10:13], v[138:141], v[212:215], v[10:13]
	v_mfma_f32_16x16x32_bf16 v[10:13], v[142:145], v[216:219], v[10:13]
	s_setprio 0
	s_setprio 1
	v_mfma_f32_16x16x32_bf16 v[54:57], v[146:149], v[184:187], v[54:57]
	v_mfma_f32_16x16x32_bf16 v[54:57], v[150:153], v[192:195], v[54:57]
	v_mfma_f32_16x16x32_bf16 v[50:53], v[174:177], v[184:187], v[50:53]
	v_mfma_f32_16x16x32_bf16 v[50:53], v[178:181], v[192:195], v[50:53]
	v_mfma_f32_16x16x32_bf16 v[38:41], v[146:149], v[196:199], v[38:41]
	v_mfma_f32_16x16x32_bf16 v[38:41], v[150:153], v[200:203], v[38:41]
	v_mfma_f32_16x16x32_bf16 v[34:37], v[174:177], v[196:199], v[34:37]
	v_mfma_f32_16x16x32_bf16 v[34:37], v[178:181], v[200:203], v[34:37]
	v_mfma_f32_16x16x32_bf16 v[22:25], v[146:149], v[204:207], v[22:25]
	v_mfma_f32_16x16x32_bf16 v[22:25], v[150:153], v[208:211], v[22:25]
	v_mfma_f32_16x16x32_bf16 v[18:21], v[174:177], v[204:207], v[18:21]
	v_mfma_f32_16x16x32_bf16 v[18:21], v[178:181], v[208:211], v[18:21]
	v_mfma_f32_16x16x32_bf16 v[6:9], v[146:149], v[212:215], v[6:9]
	v_mfma_f32_16x16x32_bf16 v[6:9], v[150:153], v[216:219], v[6:9]
	v_mfma_f32_16x16x32_bf16 v[2:5], v[174:177], v[212:215], v[2:5]
	v_mfma_f32_16x16x32_bf16 v[2:5], v[178:181], v[216:219], v[2:5]
	s_setprio 0
	s_barrier
	s_add_i32 s62, s62, 2
	s_add_u32 s26, s26, 0x100
	s_addc_u32 s27, s27, 0
	s_add_u32 s12, s12, 0x100
	s_addc_u32 s59, s59, 0
	s_cmpk_gt_u32 s62, 0xa9
	s_cbranch_scc0 .LBB0_2805
	s_and_b64 vcc, exec, s[22:23]
	s_cbranch_vccz .LBB0_2808
	s_barrier

	.amdhsa_kernel _Z9trunk_fwd4Args
		.amdhsa_group_segment_fixed_size 0
		.amdhsa_private_segment_fixed_size 0
		.amdhsa_kernarg_size 416
		.amdhsa_user_sgpr_count 2
		.amdhsa_user_sgpr_dispatch_ptr 0
		.amdhsa_user_sgpr_queue_ptr 0
		.amdhsa_user_sgpr_kernarg_segment_ptr 1
		.amdhsa_user_sgpr_dispatch_id 0
		.amdhsa_user_sgpr_kernarg_preload_length 0
		.amdhsa_user_sgpr_kernarg_preload_offset 0
		.amdhsa_user_sgpr_private_segment_size 0
		.amdhsa_uses_dynamic_stack 0
		.amdhsa_enable_private_segment 0
		.amdhsa_system_sgpr_workgroup_id_x 1
		.amdhsa_system_sgpr_workgroup_id_y 0
		.amdhsa_system_sgpr_workgroup_id_z 0
		.amdhsa_system_sgpr_workgroup_info 0
		.amdhsa_system_vgpr_workitem_id 0
		.amdhsa_next_free_vgpr 246
		.amdhsa_next_free_sgpr 102
		.amdhsa_accum_offset 248
		.amdhsa_reserve_vcc 1
		.amdhsa_float_round_mode_32 0
		.amdhsa_float_round_mode_16_64 0
		.amdhsa_float_denorm_mode_32 3
		.amdhsa_float_denorm_mode_16_64 3
		.amdhsa_dx10_clamp 1
		.amdhsa_ieee_mode 1
		.amdhsa_fp16_overflow 0
		.amdhsa_tg_split 0
		.amdhsa_exception_fp_ieee_invalid_op 0
		.amdhsa_exception_fp_denorm_src 0
		.amdhsa_exception_fp_ieee_div_zero 0
		.amdhsa_exception_fp_ieee_overflow 0
		.amdhsa_exception_fp_ieee_underflow 0
		.amdhsa_exception_fp_ieee_inexact 0
		.amdhsa_exception_int_div_zero 0
	.end_amdhsa_kernel

amdhsa.kernels:
  - .agpr_count:     0
    .args:
      - .offset:         0
        .size:           160
        .value_kind:     by_value
      - .offset:         160
        .size:           4
        .value_kind:     hidden_block_count_x
      - .offset:         164
        .size:           4
        .value_kind:     hidden_block_count_y
      - .offset:         168
        .size:           4
        .value_kind:     hidden_block_count_z
      - .offset:         172
        .size:           2
        .value_kind:     hidden_group_size_x
      - .offset:         174
        .size:           2
        .value_kind:     hidden_group_size_y
      - .offset:         176
        .size:           2
        .value_kind:     hidden_group_size_z
      - .offset:         178
        .size:           2
        .value_kind:     hidden_remainder_x
      - .offset:         180
        .size:           2
        .value_kind:     hidden_remainder_y
      - .offset:         182
        .size:           2
        .value_kind:     hidden_remainder_z
      - .offset:         200
        .size:           8
        .value_kind:     hidden_global_offset_x
      - .offset:         208
        .size:           8
        .value_kind:     hidden_global_offset_y
      - .offset:         216
        .size:           8
        .value_kind:     hidden_global_offset_z
      - .offset:         224
        .size:           2
        .value_kind:     hidden_grid_dims
      - .offset:         280
        .size:           4
        .value_kind:     hidden_dynamic_lds_size
    .group_segment_fixed_size: 0
    .kernarg_segment_align: 8
    .kernarg_segment_size: 416
    .language:       OpenCL C
    .language_version:
      - 2
      - 0
    .max_flat_workgroup_size: 512
    .name:           _Z9trunk_fwd4Args
    .private_segment_fixed_size: 0
    .sgpr_count:     108
    .sgpr_spill_count: 209
    .symbol:         _Z9trunk_fwd4Args.kd
    .uniform_work_group_size: 1
    .uses_dynamic_stack: false
    .vgpr_count:     246
    .vgpr_spill_count: 0
    .wavefront_size: 64
